# v74 + row passes: 64-lane sums by DPP instead of the __shfl_xor ds_bpermute butterflies (row1 prompt rows, sample rows of row1/row2)
# baseline (speedup 1.0000x reference)
.LBB0_1007:
	s_cmpk_gt_i32 s42, 0x7fff
	s_mov_b64 s[44:45], -1
	s_cbranch_scc0 .LBB0_1009
	s_add_i32 s0, s42, 0xffff8000
	s_lshl_b64 s[44:45], s[0:1], 12
	v_lshl_add_u64 v[166:167], v[76:77], 0, s[44:45]
	v_add_co_u32_e32 v40, vcc, 0x400000, v166
	s_waitcnt lgkmcnt(0)
	global_load_dwordx4 v[16:19], v[166:167], off offset:16
	global_load_dwordx4 v[20:23], v[166:167], off
	global_load_dwordx4 v[24:27], v[166:167], off offset:2064
	global_load_dwordx4 v[28:31], v[166:167], off offset:2048
	v_addc_co_u32_e32 v41, vcc, 0, v167, vcc
	v_add_co_u32_e32 v80, vcc, 0x800000, v166
	v_lshl_add_u64 v[36:37], v[166:167], 0, s[6:7]
	s_nop 0
	v_addc_co_u32_e32 v81, vcc, 0, v167, vcc
	v_add_co_u32_e32 v98, vcc, 0xc00000, v166
	v_lshl_add_u64 v[44:45], v[166:167], 0, s[8:9]
	s_nop 0
	v_addc_co_u32_e32 v99, vcc, 0, v167, vcc
	v_add_co_u32_e32 v114, vcc, s52, v166
	global_load_dwordx4 v[32:35], v[40:41], off
	s_nop 0
	global_load_dwordx4 v[36:39], v[36:37], off offset:16
	v_addc_co_u32_e32 v115, vcc, 0, v167, vcc
	v_add_co_u32_e32 v130, vcc, s53, v166
	global_load_dwordx4 v[40:43], v[40:41], off offset:2048
	s_nop 0
	global_load_dwordx4 v[44:47], v[44:45], off offset:16
	v_lshl_add_u64 v[52:53], v[166:167], 0, s[10:11]
	v_lshl_add_u64 v[86:87], v[166:167], 0, s[18:19]
	v_addc_co_u32_e32 v131, vcc, 0, v167, vcc
	global_load_dwordx4 v[48:51], v[80:81], off
	s_nop 0
	global_load_dwordx4 v[52:55], v[52:53], off offset:16
	s_nop 0
	global_load_dwordx4 v[80:83], v[80:81], off offset:2048
	s_nop 0
	global_load_dwordx4 v[86:89], v[86:87], off offset:16
	v_lshl_add_u64 v[94:95], v[166:167], 0, s[20:21]
	v_lshl_add_u64 v[102:103], v[166:167], 0, s[22:23]
	v_add_co_u32_e32 v146, vcc, s54, v166
	global_load_dwordx4 v[90:93], v[98:99], off
	s_nop 0
	global_load_dwordx4 v[94:97], v[94:95], off offset:16
	s_nop 0
	global_load_dwordx4 v[98:101], v[98:99], off offset:2048
	s_nop 0
	global_load_dwordx4 v[102:105], v[102:103], off offset:16
	v_lshl_add_u64 v[110:111], v[166:167], 0, s[24:25]
	v_lshl_add_u64 v[118:119], v[166:167], 0, s[26:27]
	v_addc_co_u32_e32 v147, vcc, 0, v167, vcc
	global_load_dwordx4 v[106:109], v[114:115], off
	s_nop 0
	global_load_dwordx4 v[110:113], v[110:111], off offset:16
	s_nop 0
	global_load_dwordx4 v[114:117], v[114:115], off offset:2048
	s_nop 0
	global_load_dwordx4 v[118:121], v[118:119], off offset:16
	v_lshl_add_u64 v[126:127], v[166:167], 0, s[28:29]
	v_lshl_add_u64 v[134:135], v[166:167], 0, s[30:31]
	v_add_co_u32_e32 v162, vcc, s55, v166
	global_load_dwordx4 v[122:125], v[130:131], off
	s_nop 0
	global_load_dwordx4 v[126:129], v[126:127], off offset:16
	s_nop 0
	global_load_dwordx4 v[130:133], v[130:131], off offset:2048
	s_nop 0
	global_load_dwordx4 v[134:137], v[134:135], off offset:16
	v_lshl_add_u64 v[142:143], v[166:167], 0, s[34:35]
	v_lshl_add_u64 v[150:151], v[166:167], 0, s[36:37]
	v_addc_co_u32_e32 v163, vcc, 0, v167, vcc
	global_load_dwordx4 v[138:141], v[146:147], off
	s_nop 0
	global_load_dwordx4 v[142:145], v[142:143], off offset:16
	s_nop 0
	global_load_dwordx4 v[146:149], v[146:147], off offset:2048
	s_nop 0
	global_load_dwordx4 v[150:153], v[150:151], off offset:16
	v_lshl_add_u64 v[158:159], v[166:167], 0, s[38:39]
	global_load_dwordx4 v[154:157], v[162:163], off
	s_nop 0
	global_load_dwordx4 v[158:161], v[158:159], off offset:16
	s_nop 0
	global_load_dwordx4 v[162:165], v[162:163], off offset:2048
	v_lshl_add_u64 v[166:167], v[166:167], 0, s[40:41]
	global_load_dwordx4 v[166:169], v[166:167], off offset:16
	s_mov_b32 s43, s1
	s_lshl_b64 s[46:47], s[42:43], 11
	s_mov_b64 s[44:45], 0
	s_waitcnt vmcnt(31)
	v_pk_add_f32 v[18:19], v[18:19], 0 op_sel_hi:[1,0]
	s_waitcnt vmcnt(30)
	v_pk_add_f32 v[22:23], v[22:23], 0 op_sel_hi:[1,0]
	v_pk_add_f32 v[20:21], v[20:21], 0 op_sel_hi:[1,0]
	v_pk_add_f32 v[16:17], v[16:17], 0 op_sel_hi:[1,0]
	s_waitcnt vmcnt(28)
	v_pk_add_f32 v[30:31], v[30:31], 0 op_sel_hi:[1,0]
	v_pk_add_f32 v[28:29], v[28:29], 0 op_sel_hi:[1,0]
	v_pk_add_f32 v[26:27], v[26:27], 0 op_sel_hi:[1,0]
	v_pk_add_f32 v[24:25], v[24:25], 0 op_sel_hi:[1,0]
	s_waitcnt vmcnt(27)
	v_pk_add_f32 v[22:23], v[22:23], v[34:35]
	v_pk_add_f32 v[20:21], v[20:21], v[32:33]
	s_waitcnt vmcnt(26)
	v_pk_add_f32 v[18:19], v[18:19], v[38:39]
	v_pk_add_f32 v[16:17], v[16:17], v[36:37]
	s_waitcnt vmcnt(25)
	v_pk_add_f32 v[30:31], v[30:31], v[42:43]
	v_pk_add_f32 v[28:29], v[28:29], v[40:41]
	s_waitcnt vmcnt(24)
	v_pk_add_f32 v[26:27], v[26:27], v[46:47]
	v_pk_add_f32 v[24:25], v[24:25], v[44:45]
	s_waitcnt vmcnt(23)
	v_pk_add_f32 v[22:23], v[22:23], v[50:51]
	v_pk_add_f32 v[20:21], v[20:21], v[48:49]
	s_waitcnt vmcnt(22)
	v_pk_add_f32 v[18:19], v[18:19], v[54:55]
	v_pk_add_f32 v[16:17], v[16:17], v[52:53]
	s_waitcnt vmcnt(21)
	v_pk_add_f32 v[30:31], v[30:31], v[82:83]
	v_pk_add_f32 v[28:29], v[28:29], v[80:81]
	s_waitcnt vmcnt(20)
	v_pk_add_f32 v[26:27], v[26:27], v[88:89]
	v_pk_add_f32 v[24:25], v[24:25], v[86:87]
	s_waitcnt vmcnt(19)
	v_pk_add_f32 v[22:23], v[22:23], v[92:93]
	v_pk_add_f32 v[20:21], v[20:21], v[90:91]
	s_waitcnt vmcnt(18)
	v_pk_add_f32 v[18:19], v[18:19], v[96:97]
	v_pk_add_f32 v[16:17], v[16:17], v[94:95]
	s_waitcnt vmcnt(17)
	v_pk_add_f32 v[30:31], v[30:31], v[100:101]
	v_pk_add_f32 v[28:29], v[28:29], v[98:99]
	s_waitcnt vmcnt(16)
	v_pk_add_f32 v[26:27], v[26:27], v[104:105]
	v_pk_add_f32 v[24:25], v[24:25], v[102:103]
	s_waitcnt vmcnt(15)
	v_pk_add_f32 v[22:23], v[22:23], v[108:109]
	v_pk_add_f32 v[20:21], v[20:21], v[106:107]
	s_waitcnt vmcnt(14)
	v_pk_add_f32 v[18:19], v[18:19], v[112:113]
	v_pk_add_f32 v[16:17], v[16:17], v[110:111]
	s_waitcnt vmcnt(13)
	v_pk_add_f32 v[30:31], v[30:31], v[116:117]
	v_pk_add_f32 v[28:29], v[28:29], v[114:115]
	s_waitcnt vmcnt(12)
	v_pk_add_f32 v[26:27], v[26:27], v[120:121]
	v_pk_add_f32 v[24:25], v[24:25], v[118:119]
	s_waitcnt vmcnt(11)
	v_pk_add_f32 v[22:23], v[22:23], v[124:125]
	v_pk_add_f32 v[20:21], v[20:21], v[122:123]
	s_waitcnt vmcnt(10)
	v_pk_add_f32 v[18:19], v[18:19], v[128:129]
	v_pk_add_f32 v[16:17], v[16:17], v[126:127]
	s_waitcnt vmcnt(9)
	v_pk_add_f32 v[30:31], v[30:31], v[132:133]
	v_pk_add_f32 v[28:29], v[28:29], v[130:131]
	s_waitcnt vmcnt(8)
	v_pk_add_f32 v[26:27], v[26:27], v[136:137]
	v_pk_add_f32 v[24:25], v[24:25], v[134:135]
	s_waitcnt vmcnt(7)
	v_pk_add_f32 v[22:23], v[22:23], v[140:141]
	v_pk_add_f32 v[20:21], v[20:21], v[138:139]
	s_waitcnt vmcnt(6)
	v_pk_add_f32 v[18:19], v[18:19], v[144:145]
	v_pk_add_f32 v[16:17], v[16:17], v[142:143]
	s_waitcnt vmcnt(5)
	v_pk_add_f32 v[32:33], v[30:31], v[148:149]
	v_pk_add_f32 v[34:35], v[28:29], v[146:147]
	s_waitcnt vmcnt(4)
	v_pk_add_f32 v[36:37], v[26:27], v[152:153]
	v_pk_add_f32 v[38:39], v[24:25], v[150:151]
	s_waitcnt vmcnt(3)
	v_pk_add_f32 v[26:27], v[22:23], v[156:157]
	v_pk_add_f32 v[24:25], v[20:21], v[154:155]
	s_waitcnt vmcnt(2)
	v_pk_add_f32 v[30:31], v[18:19], v[160:161]
	v_pk_add_f32 v[28:29], v[16:17], v[158:159]
	s_waitcnt vmcnt(1)
	v_pk_add_f32 v[18:19], v[32:33], v[164:165]
	v_pk_add_f32 v[16:17], v[34:35], v[162:163]
	v_pk_mul_f32 v[32:33], v[26:27], v[26:27]
	v_pk_mul_f32 v[34:35], v[24:25], v[24:25]
	s_waitcnt vmcnt(0)
	v_pk_add_f32 v[22:23], v[36:37], v[168:169]
	v_pk_mov_b32 v[36:37], v[34:35], v[32:33] op_sel:[1,0]
	v_mov_b32_e32 v35, v33
	v_pk_add_f32 v[32:33], v[36:37], v[34:35]
	v_pk_mul_f32 v[34:35], v[30:31], v[30:31]
	v_pk_mul_f32 v[36:37], v[28:29], v[28:29]
	v_pk_add_f32 v[20:21], v[38:39], v[166:167]
	v_pk_mov_b32 v[38:39], v[36:37], v[34:35] op_sel:[1,0]
	v_mov_b32_e32 v37, v35
	v_pk_add_f32 v[34:35], v[38:39], v[36:37]
	v_mul_f32_e32 v36, v20, v20
	v_mul_f32_e32 v37, v21, v21
	v_pk_add_f32 v[32:33], v[32:33], v[32:33] op_sel:[0,1] op_sel_hi:[1,0]
	v_pk_add_f32 v[34:35], v[34:35], v[34:35] op_sel:[0,1] op_sel_hi:[1,0]
	v_mov_b32_e32 v33, v36
	v_mov_b32_e32 v35, v37
	v_pk_add_f32 v[32:33], v[32:33], v[34:35]
	v_mul_f32_e32 v34, v17, v17
	v_mul_f32_e32 v36, v19, v19
	v_mul_f32_e32 v38, v22, v22
	v_mul_f32_e32 v39, v23, v23
	v_pk_fma_f32 v[34:35], v[16:17], v[16:17], v[34:35] op_sel_hi:[1,1,0]
	v_pk_fma_f32 v[36:37], v[18:19], v[18:19], v[36:37] op_sel_hi:[1,1,0]
	v_mov_b32_e32 v35, v38
	v_mov_b32_e32 v37, v39
	v_pk_add_f32 v[34:35], v[34:35], v[36:37]
	s_nop 0
	v_pk_add_f32 v[32:33], v[32:33], v[34:35]
	v_xor_b32_e32 v34, 1, v84
	v_add_f32_e32 v32, v32, v33
	v_and_b32_e32 v33, 64, v84
	v_add_u32_e32 v33, 64, v33
	v_cmp_lt_i32_e32 vcc, v34, v33
	s_nop 1
	v_cndmask_b32_e32 v34, v84, v34, vcc
	v_lshlrev_b32_e32 v34, 2, v34
	v_mov_b32_e32 v240, v32
	s_nop 1
	v_add_f32_dpp v240, v240, v240 quad_perm:[1,0,3,2] row_mask:0xf bank_mask:0xf
	s_nop 1
	v_add_f32_dpp v240, v240, v240 quad_perm:[2,3,0,1] row_mask:0xf bank_mask:0xf
	s_nop 1
	v_add_f32_dpp v240, v240, v240 row_half_mirror row_mask:0xf bank_mask:0xf
	s_nop 1
	v_add_f32_dpp v240, v240, v240 row_mirror row_mask:0xf bank_mask:0xf
	s_nop 1
	v_add_f32_dpp v240, v240, v240 row_bcast:15 row_mask:0xa bank_mask:0xf
	s_nop 1
	v_add_f32_dpp v240, v240, v240 row_bcast:31 row_mask:0xc bank_mask:0xf
	s_nop 1
	v_readlane_b32 s98, v240, 63
	s_nop 1
	v_xor_b32_e32 v34, 2, v84
	v_cmp_lt_i32_e32 vcc, v34, v33
	s_nop 1
	v_cndmask_b32_e32 v34, v84, v34, vcc
	v_lshlrev_b32_e32 v34, 2, v34
	v_xor_b32_e32 v34, 4, v84
	v_cmp_lt_i32_e32 vcc, v34, v33
	s_nop 1
	v_cndmask_b32_e32 v34, v84, v34, vcc
	v_lshlrev_b32_e32 v34, 2, v34
	v_xor_b32_e32 v34, 8, v84
	v_cmp_lt_i32_e32 vcc, v34, v33
	s_nop 1
	v_cndmask_b32_e32 v34, v84, v34, vcc
	v_lshlrev_b32_e32 v34, 2, v34
	v_xor_b32_e32 v34, 16, v84
	v_cmp_lt_i32_e32 vcc, v34, v33
	s_nop 1
	v_cndmask_b32_e32 v34, v84, v34, vcc
	v_lshlrev_b32_e32 v34, 2, v34
	v_xor_b32_e32 v34, 32, v84
	v_cmp_lt_i32_e32 vcc, v34, v33
	s_nop 1
	v_cndmask_b32_e32 v33, v84, v34, vcc
	v_lshlrev_b32_e32 v33, 2, v33
	v_mov_b32_e32 v85, s98

.LBB0_1011:
	s_add_i32 s56, s42, s85
	s_cmp_lt_i32 s56, 0x8400
	s_cselect_b32 s44, s56, s42
	s_lshl_b64 s[42:43], s[42:43], 2
	v_lshl_add_u64 v[80:81], v[74:75], 0, s[46:47]
	s_add_u32 s46, s33, s42
	s_addc_u32 s47, s50, s43
	global_load_dwordx4 v[52:55], v[80:81], off
	global_load_dwordx4 v[48:51], v[80:81], off offset:1024
	global_load_dword v82, v57, s[46:47]
	s_cmp_lt_i32 s44, 0x8000
	s_mov_b64 s[48:49], -1
	s_cbranch_scc1 .LBB0_1013
	s_add_i32 s0, s44, 0xffff8000
	s_lshl_b64 s[46:47], s[0:1], 12
	v_lshl_add_u64 v[196:197], v[76:77], 0, s[46:47]
	v_add_co_u32_e32 v94, vcc, 0x400000, v196
	global_load_dwordx4 v[32:35], v[196:197], off offset:16
	global_load_dwordx4 v[36:39], v[196:197], off
	global_load_dwordx4 v[40:43], v[196:197], off offset:2064
	global_load_dwordx4 v[44:47], v[196:197], off offset:2048
	v_addc_co_u32_e32 v95, vcc, 0, v197, vcc
	v_add_co_u32_e32 v110, vcc, 0x800000, v196
	v_lshl_add_u64 v[90:91], v[196:197], 0, s[6:7]
	s_nop 0
	v_addc_co_u32_e32 v111, vcc, 0, v197, vcc
	v_add_co_u32_e32 v126, vcc, 0xc00000, v196
	v_lshl_add_u64 v[98:99], v[196:197], 0, s[8:9]
	s_nop 0
	v_addc_co_u32_e32 v127, vcc, 0, v197, vcc
	v_add_co_u32_e32 v142, vcc, s52, v196
	global_load_dwordx4 v[86:89], v[94:95], off
	s_nop 0
	global_load_dwordx4 v[90:93], v[90:91], off offset:16
	v_addc_co_u32_e32 v143, vcc, 0, v197, vcc
	v_add_co_u32_e32 v158, vcc, s53, v196
	global_load_dwordx4 v[94:97], v[94:95], off offset:2048
	s_nop 0
	global_load_dwordx4 v[98:101], v[98:99], off offset:16
	v_lshl_add_u64 v[106:107], v[196:197], 0, s[10:11]
	v_lshl_add_u64 v[114:115], v[196:197], 0, s[18:19]
	v_addc_co_u32_e32 v159, vcc, 0, v197, vcc
	global_load_dwordx4 v[102:105], v[110:111], off
	s_nop 0
	global_load_dwordx4 v[106:109], v[106:107], off offset:16
	s_nop 0
	global_load_dwordx4 v[110:113], v[110:111], off offset:2048
	s_nop 0
	global_load_dwordx4 v[114:117], v[114:115], off offset:16
	v_lshl_add_u64 v[122:123], v[196:197], 0, s[20:21]
	v_lshl_add_u64 v[130:131], v[196:197], 0, s[22:23]
	v_add_co_u32_e32 v174, vcc, s54, v196
	global_load_dwordx4 v[118:121], v[126:127], off
	s_nop 0
	global_load_dwordx4 v[122:125], v[122:123], off offset:16
	s_nop 0
	global_load_dwordx4 v[126:129], v[126:127], off offset:2048
	s_nop 0
	global_load_dwordx4 v[130:133], v[130:131], off offset:16
	v_lshl_add_u64 v[138:139], v[196:197], 0, s[24:25]
	v_lshl_add_u64 v[146:147], v[196:197], 0, s[26:27]
	v_addc_co_u32_e32 v175, vcc, 0, v197, vcc
	global_load_dwordx4 v[134:137], v[142:143], off
	s_nop 0
	global_load_dwordx4 v[138:141], v[138:139], off offset:16
	s_nop 0
	global_load_dwordx4 v[142:145], v[142:143], off offset:2048
	s_nop 0
	global_load_dwordx4 v[146:149], v[146:147], off offset:16
	v_lshl_add_u64 v[154:155], v[196:197], 0, s[28:29]
	v_lshl_add_u64 v[162:163], v[196:197], 0, s[30:31]
	v_add_co_u32_e32 v192, vcc, s55, v196
	global_load_dwordx4 v[150:153], v[158:159], off
	s_nop 0
	global_load_dwordx4 v[154:157], v[154:155], off offset:16
	s_nop 0
	global_load_dwordx4 v[158:161], v[158:159], off offset:2048
	s_nop 0
	global_load_dwordx4 v[162:165], v[162:163], off offset:16
	v_lshl_add_u64 v[170:171], v[196:197], 0, s[34:35]
	v_lshl_add_u64 v[180:181], v[196:197], 0, s[36:37]
	v_addc_co_u32_e32 v193, vcc, 0, v197, vcc
	global_load_dwordx4 v[166:169], v[174:175], off
	s_nop 0
	global_load_dwordx4 v[170:173], v[170:171], off offset:16
	s_nop 0
	global_load_dwordx4 v[174:177], v[174:175], off offset:2048
	s_nop 0
	global_load_dwordx4 v[180:183], v[180:181], off offset:16
	v_lshl_add_u64 v[188:189], v[196:197], 0, s[38:39]
	global_load_dwordx4 v[184:187], v[192:193], off
	s_nop 0
	global_load_dwordx4 v[188:191], v[188:189], off offset:16
	s_nop 0
	global_load_dwordx4 v[192:195], v[192:193], off offset:2048
	v_lshl_add_u64 v[196:197], v[196:197], 0, s[40:41]
	global_load_dwordx4 v[196:199], v[196:197], off offset:16
	s_mov_b32 s45, s1
	s_lshl_b64 s[46:47], s[44:45], 11
	s_mov_b64 s[48:49], 0
	s_waitcnt vmcnt(31)
	v_pk_add_f32 v[34:35], v[34:35], 0 op_sel_hi:[1,0]
	s_waitcnt vmcnt(30)
	v_pk_add_f32 v[38:39], v[38:39], 0 op_sel_hi:[1,0]
	v_pk_add_f32 v[36:37], v[36:37], 0 op_sel_hi:[1,0]
	v_pk_add_f32 v[32:33], v[32:33], 0 op_sel_hi:[1,0]
	s_waitcnt vmcnt(28)
	v_pk_add_f32 v[46:47], v[46:47], 0 op_sel_hi:[1,0]
	v_pk_add_f32 v[44:45], v[44:45], 0 op_sel_hi:[1,0]
	v_pk_add_f32 v[42:43], v[42:43], 0 op_sel_hi:[1,0]
	v_pk_add_f32 v[40:41], v[40:41], 0 op_sel_hi:[1,0]
	s_waitcnt vmcnt(27)
	v_pk_add_f32 v[38:39], v[38:39], v[88:89]
	v_pk_add_f32 v[36:37], v[36:37], v[86:87]
	s_waitcnt vmcnt(26)
	v_pk_add_f32 v[34:35], v[34:35], v[92:93]
	v_pk_add_f32 v[32:33], v[32:33], v[90:91]
	s_waitcnt vmcnt(25)
	v_pk_add_f32 v[46:47], v[46:47], v[96:97]
	v_pk_add_f32 v[44:45], v[44:45], v[94:95]
	s_waitcnt vmcnt(24)
	v_pk_add_f32 v[42:43], v[42:43], v[100:101]
	v_pk_add_f32 v[40:41], v[40:41], v[98:99]
	s_waitcnt vmcnt(23)
	v_pk_add_f32 v[38:39], v[38:39], v[104:105]
	v_pk_add_f32 v[36:37], v[36:37], v[102:103]
	s_waitcnt vmcnt(22)
	v_pk_add_f32 v[34:35], v[34:35], v[108:109]
	v_pk_add_f32 v[32:33], v[32:33], v[106:107]
	s_waitcnt vmcnt(21)
	v_pk_add_f32 v[46:47], v[46:47], v[112:113]
	v_pk_add_f32 v[44:45], v[44:45], v[110:111]
	s_waitcnt vmcnt(20)
	v_pk_add_f32 v[42:43], v[42:43], v[116:117]
	v_pk_add_f32 v[40:41], v[40:41], v[114:115]
	s_waitcnt vmcnt(19)
	v_pk_add_f32 v[38:39], v[38:39], v[120:121]
	v_pk_add_f32 v[36:37], v[36:37], v[118:119]
	s_waitcnt vmcnt(18)
	v_pk_add_f32 v[34:35], v[34:35], v[124:125]
	v_pk_add_f32 v[32:33], v[32:33], v[122:123]
	s_waitcnt vmcnt(17)
	v_pk_add_f32 v[46:47], v[46:47], v[128:129]
	v_pk_add_f32 v[44:45], v[44:45], v[126:127]
	s_waitcnt vmcnt(16)
	v_pk_add_f32 v[42:43], v[42:43], v[132:133]
	v_pk_add_f32 v[40:41], v[40:41], v[130:131]
	s_waitcnt vmcnt(15)
	v_pk_add_f32 v[38:39], v[38:39], v[136:137]
	v_pk_add_f32 v[36:37], v[36:37], v[134:135]
	s_waitcnt vmcnt(14)
	v_pk_add_f32 v[34:35], v[34:35], v[140:141]
	v_pk_add_f32 v[32:33], v[32:33], v[138:139]
	s_waitcnt vmcnt(13)
	v_pk_add_f32 v[46:47], v[46:47], v[144:145]
	v_pk_add_f32 v[44:45], v[44:45], v[142:143]
	s_waitcnt vmcnt(12)
	v_pk_add_f32 v[42:43], v[42:43], v[148:149]
	v_pk_add_f32 v[40:41], v[40:41], v[146:147]
	s_waitcnt vmcnt(11)
	v_pk_add_f32 v[38:39], v[38:39], v[152:153]
	v_pk_add_f32 v[36:37], v[36:37], v[150:151]
	s_waitcnt vmcnt(10)
	v_pk_add_f32 v[34:35], v[34:35], v[156:157]
	v_pk_add_f32 v[32:33], v[32:33], v[154:155]
	s_waitcnt vmcnt(9)
	v_pk_add_f32 v[46:47], v[46:47], v[160:161]
	v_pk_add_f32 v[44:45], v[44:45], v[158:159]
	s_waitcnt vmcnt(8)
	v_pk_add_f32 v[42:43], v[42:43], v[164:165]
	v_pk_add_f32 v[40:41], v[40:41], v[162:163]
	s_waitcnt vmcnt(7)
	v_pk_add_f32 v[38:39], v[38:39], v[168:169]
	v_pk_add_f32 v[36:37], v[36:37], v[166:167]
	s_waitcnt vmcnt(6)
	v_pk_add_f32 v[34:35], v[34:35], v[172:173]
	v_pk_add_f32 v[32:33], v[32:33], v[170:171]
	s_waitcnt vmcnt(5)
	v_pk_add_f32 v[86:87], v[46:47], v[176:177]
	v_pk_add_f32 v[88:89], v[44:45], v[174:175]
	s_waitcnt vmcnt(4)
	v_pk_add_f32 v[90:91], v[42:43], v[182:183]
	v_pk_add_f32 v[92:93], v[40:41], v[180:181]
	s_waitcnt vmcnt(3)
	v_pk_add_f32 v[42:43], v[38:39], v[186:187]
	v_pk_add_f32 v[40:41], v[36:37], v[184:185]
	s_waitcnt vmcnt(2)
	v_pk_add_f32 v[46:47], v[34:35], v[190:191]
	v_pk_add_f32 v[44:45], v[32:33], v[188:189]
	s_waitcnt vmcnt(1)
	v_pk_add_f32 v[34:35], v[86:87], v[194:195]
	v_pk_add_f32 v[32:33], v[88:89], v[192:193]
	v_pk_mul_f32 v[86:87], v[42:43], v[42:43]
	v_pk_mul_f32 v[88:89], v[40:41], v[40:41]
	s_waitcnt vmcnt(0)
	v_pk_add_f32 v[38:39], v[90:91], v[198:199]
	v_pk_mov_b32 v[90:91], v[88:89], v[86:87] op_sel:[1,0]
	v_mov_b32_e32 v89, v87
	v_pk_add_f32 v[86:87], v[90:91], v[88:89]
	v_pk_mul_f32 v[88:89], v[46:47], v[46:47]
	v_pk_mul_f32 v[90:91], v[44:45], v[44:45]
	v_pk_add_f32 v[36:37], v[92:93], v[196:197]
	v_pk_mov_b32 v[92:93], v[90:91], v[88:89] op_sel:[1,0]
	v_mov_b32_e32 v91, v89
	v_pk_add_f32 v[88:89], v[92:93], v[90:91]
	v_mul_f32_e32 v83, v36, v36
	v_mul_f32_e32 v90, v37, v37
	v_pk_add_f32 v[86:87], v[86:87], v[86:87] op_sel:[0,1] op_sel_hi:[1,0]
	v_pk_add_f32 v[88:89], v[88:89], v[88:89] op_sel:[0,1] op_sel_hi:[1,0]
	v_mov_b32_e32 v87, v83
	v_mov_b32_e32 v89, v90
	v_pk_add_f32 v[86:87], v[86:87], v[88:89]
	v_mul_f32_e32 v88, v33, v33
	v_mul_f32_e32 v91, v38, v38
	v_pk_fma_f32 v[88:89], v[32:33], v[32:33], v[88:89] op_sel_hi:[1,1,0]
	v_mul_f32_e32 v90, v35, v35
	v_mul_f32_e32 v92, v39, v39
	v_mov_b32_e32 v89, v91
	v_pk_fma_f32 v[90:91], v[34:35], v[34:35], v[90:91] op_sel_hi:[1,1,0]
	s_nop 0
	v_mov_b32_e32 v91, v92
	v_pk_add_f32 v[88:89], v[88:89], v[90:91]
	s_nop 0
	v_pk_add_f32 v[86:87], v[86:87], v[88:89]
	s_nop 0
	v_add_f32_e32 v83, v86, v87
	v_and_b32_e32 v86, 64, v84
	v_add_u32_e32 v86, 64, v86
	v_xor_b32_e32 v87, 1, v84
	v_cmp_lt_i32_e32 vcc, v87, v86
	s_nop 1
	v_cndmask_b32_e32 v87, v84, v87, vcc
	v_lshlrev_b32_e32 v87, 2, v87
	v_mov_b32_e32 v241, v83
	s_nop 1
	v_add_f32_dpp v241, v241, v241 quad_perm:[1,0,3,2] row_mask:0xf bank_mask:0xf
	s_nop 1
	v_add_f32_dpp v241, v241, v241 quad_perm:[2,3,0,1] row_mask:0xf bank_mask:0xf
	s_nop 1
	v_add_f32_dpp v241, v241, v241 row_half_mirror row_mask:0xf bank_mask:0xf
	s_nop 1
	v_add_f32_dpp v241, v241, v241 row_mirror row_mask:0xf bank_mask:0xf
	s_nop 1
	v_add_f32_dpp v241, v241, v241 row_bcast:15 row_mask:0xa bank_mask:0xf
	s_nop 1
	v_add_f32_dpp v241, v241, v241 row_bcast:31 row_mask:0xc bank_mask:0xf
	s_nop 1
	v_readlane_b32 s99, v241, 63
	s_nop 1
	v_xor_b32_e32 v87, 2, v84
	v_cmp_lt_i32_e32 vcc, v87, v86
	s_nop 1
	v_cndmask_b32_e32 v87, v84, v87, vcc
	v_lshlrev_b32_e32 v87, 2, v87
	v_xor_b32_e32 v87, 4, v84
	v_cmp_lt_i32_e32 vcc, v87, v86
	s_nop 1
	v_cndmask_b32_e32 v87, v84, v87, vcc
	v_lshlrev_b32_e32 v87, 2, v87
	v_xor_b32_e32 v87, 8, v84
	v_cmp_lt_i32_e32 vcc, v87, v86
	s_nop 1
	v_cndmask_b32_e32 v87, v84, v87, vcc
	v_lshlrev_b32_e32 v87, 2, v87
	v_xor_b32_e32 v87, 16, v84
	v_cmp_lt_i32_e32 vcc, v87, v86
	s_nop 1
	v_cndmask_b32_e32 v87, v84, v87, vcc
	v_lshlrev_b32_e32 v87, 2, v87
	v_xor_b32_e32 v87, 32, v84
	v_cmp_lt_i32_e32 vcc, v87, v86
	s_nop 1
	v_cndmask_b32_e32 v86, v84, v87, vcc
	v_lshlrev_b32_e32 v86, 2, v86
	v_mov_b32_e32 v86, s99

.LBB0_1015:
	s_waitcnt vmcnt(0)
	v_div_scale_f32 v83, s[48:49], v82, v82, 1.0
	v_rcp_f32_e32 v87, v83
	v_lshlrev_b32_e32 v88, 16, v52
	v_and_b32_e32 v89, 0xffff0000, v52
	v_lshlrev_b32_e32 v52, 16, v53
	v_fma_f32 v96, -v83, v87, 1.0
	v_fmac_f32_e32 v87, v96, v87
	v_div_scale_f32 v96, vcc, 1.0, v82, 1.0
	v_mul_f32_e32 v97, v96, v87
	v_fma_f32 v98, -v83, v97, v96
	v_fmac_f32_e32 v97, v98, v87
	v_fma_f32 v83, -v83, v97, v96
	v_div_fmas_f32 v83, v83, v87, v97
	v_and_b32_e32 v53, 0xffff0000, v53
	v_lshlrev_b32_e32 v90, 16, v54
	v_and_b32_e32 v91, 0xffff0000, v54
	v_lshlrev_b32_e32 v54, 16, v55
	v_and_b32_e32 v55, 0xffff0000, v55
	v_lshlrev_b32_e32 v92, 16, v48
	v_and_b32_e32 v93, 0xffff0000, v48
	v_lshlrev_b32_e32 v48, 16, v49
	v_and_b32_e32 v49, 0xffff0000, v49
	v_lshlrev_b32_e32 v94, 16, v50
	v_and_b32_e32 v95, 0xffff0000, v50
	v_lshlrev_b32_e32 v50, 16, v51
	v_and_b32_e32 v51, 0xffff0000, v51
	v_div_fixup_f32 v82, v83, v82, 1.0
	s_lshl_b64 s[44:45], s[44:45], 2
	v_fmamk_f32 v85, v85, 0x3a800000, v56
	v_pk_mul_f32 v[88:89], v[82:83], v[88:89] op_sel_hi:[0,1]
	v_pk_mul_f32 v[96:97], v[82:83], v[52:53] op_sel_hi:[0,1]
	v_pk_mul_f32 v[90:91], v[82:83], v[90:91] op_sel_hi:[0,1]
	v_pk_mul_f32 v[98:99], v[82:83], v[54:55] op_sel_hi:[0,1]
	v_pk_mul_f32 v[92:93], v[82:83], v[92:93] op_sel_hi:[0,1]
	v_pk_mul_f32 v[100:101], v[82:83], v[48:49] op_sel_hi:[0,1]
	v_pk_mul_f32 v[94:95], v[82:83], v[94:95] op_sel_hi:[0,1]
	v_pk_mul_f32 v[102:103], v[82:83], v[50:51] op_sel_hi:[0,1]
	v_lshl_add_u64 v[82:83], v[74:75], 0, s[46:47]
	v_mul_f32_e32 v87, 0x4b800000, v85
	v_cmp_gt_f32_e32 vcc, s51, v85
	s_add_u32 s46, s33, s44
	s_addc_u32 s47, s50, s45
	v_cndmask_b32_e32 v85, v85, v87, vcc
	global_load_dwordx4 v[52:55], v[82:83], off
	global_load_dwordx4 v[48:51], v[82:83], off offset:1024
	v_rsq_f32_e32 v87, v85
	global_load_dword v85, v57, s[46:47]
	v_mul_f32_e32 v104, 0x45800000, v87
	v_cndmask_b32_e32 v104, v87, v104, vcc
	v_pk_mul_f32 v[26:27], v[26:27], v[104:105] op_sel_hi:[1,0]
	v_pk_mul_f32 v[24:25], v[24:25], v[104:105] op_sel_hi:[1,0]
	v_pk_mul_f32 v[26:27], v[6:7], v[26:27]
	v_pk_mul_f32 v[24:25], v[4:5], v[24:25]
	v_pk_fma_f32 v[26:27], v[60:61], v[96:97], v[26:27]
	v_pk_fma_f32 v[24:25], v[58:59], v[88:89], v[24:25]
	v_pk_mul_f32 v[30:31], v[30:31], v[104:105] op_sel_hi:[1,0]
	v_pk_mul_f32 v[28:29], v[28:29], v[104:105] op_sel_hi:[1,0]
	v_pk_mul_f32 v[30:31], v[2:3], v[30:31]
	v_pk_mul_f32 v[28:29], v[0:1], v[28:29]
	v_mul_f32_e32 v87, v25, v25
	v_mul_f32_e32 v88, v27, v27
	v_pk_fma_f32 v[30:31], v[64:65], v[98:99], v[30:31]
	v_pk_fma_f32 v[28:29], v[62:63], v[90:91], v[28:29]
	v_fmac_f32_e32 v87, v24, v24
	v_fmac_f32_e32 v88, v26, v26
	v_add_f32_e32 v87, v87, v88
	v_mul_f32_e32 v88, v29, v29
	v_mul_f32_e32 v89, v31, v31
	s_waitcnt lgkmcnt(0)
	v_pk_mul_f32 v[16:17], v[16:17], v[104:105] op_sel_hi:[1,0]
	v_fmac_f32_e32 v88, v28, v28
	v_fmac_f32_e32 v89, v30, v30
	v_pk_mul_f32 v[18:19], v[18:19], v[104:105] op_sel_hi:[1,0]
	v_pk_mul_f32 v[16:17], v[12:13], v[16:17]
	v_add_f32_e32 v88, v88, v89
	v_pk_mul_f32 v[18:19], v[14:15], v[18:19]
	v_pk_fma_f32 v[90:91], v[66:67], v[92:93], v[16:17]
	v_pk_mul_f32 v[16:17], v[22:23], v[104:105] op_sel_hi:[1,0]
	v_add_f32_e32 v87, v87, v88
	v_pk_fma_f32 v[88:89], v[68:69], v[100:101], v[18:19]
	v_pk_mul_f32 v[18:19], v[20:21], v[104:105] op_sel_hi:[1,0]
	v_pk_mul_f32 v[16:17], v[10:11], v[16:17]
	v_pk_mul_f32 v[18:19], v[8:9], v[18:19]
	v_pk_fma_f32 v[92:93], v[72:73], v[102:103], v[16:17]
	v_mul_f32_e32 v16, v91, v91
	v_mul_f32_e32 v17, v89, v89
	v_pk_fma_f32 v[94:95], v[70:71], v[94:95], v[18:19]
	v_fmac_f32_e32 v16, v90, v90
	v_fmac_f32_e32 v17, v88, v88
	v_add_f32_e32 v16, v16, v17
	v_mul_f32_e32 v17, v95, v95
	v_mul_f32_e32 v18, v93, v93
	v_fmac_f32_e32 v17, v94, v94
	v_fmac_f32_e32 v18, v92, v92
	v_add_f32_e32 v16, v16, v87
	v_add_f32_e32 v17, v17, v18
	v_add_f32_e32 v17, v17, v16
	v_and_b32_e32 v16, 64, v84
	v_add_u32_e32 v21, 64, v16
	v_xor_b32_e32 v16, 1, v84
	v_cmp_lt_i32_e32 vcc, v16, v21
	v_cvt_pk_bf16_f32 v22, v24, v25
	v_cvt_pk_bf16_f32 v23, v26, v27
	v_cvt_pk_bf16_f32 v24, v28, v29
	v_cvt_pk_bf16_f32 v25, v30, v31
	global_store_dwordx4 v[80:81], v[22:25], off
	s_nop 0
	v_cndmask_b32_e32 v16, v84, v16, vcc
	v_lshlrev_b32_e32 v16, 2, v16
	v_mov_b32_e32 v242, v17
	s_nop 1
	v_add_f32_dpp v242, v242, v242 quad_perm:[1,0,3,2] row_mask:0xf bank_mask:0xf
	s_nop 1
	v_add_f32_dpp v242, v242, v242 quad_perm:[2,3,0,1] row_mask:0xf bank_mask:0xf
	s_nop 1
	v_add_f32_dpp v242, v242, v242 row_half_mirror row_mask:0xf bank_mask:0xf
	s_nop 1
	v_add_f32_dpp v242, v242, v242 row_mirror row_mask:0xf bank_mask:0xf
	s_nop 1
	v_add_f32_dpp v242, v242, v242 row_bcast:15 row_mask:0xa bank_mask:0xf
	s_nop 1
	v_add_f32_dpp v242, v242, v242 row_bcast:31 row_mask:0xc bank_mask:0xf
	s_nop 1
	v_readlane_b32 s100, v242, 63
	s_nop 1
	v_xor_b32_e32 v23, 32, v84
	v_cvt_pk_bf16_f32 v24, v90, v91
	v_cvt_pk_bf16_f32 v25, v88, v89
	v_xor_b32_e32 v17, 2, v84
	v_cmp_lt_i32_e32 vcc, v17, v21
	s_nop 1
	v_cndmask_b32_e32 v17, v84, v17, vcc
	v_lshlrev_b32_e32 v17, 2, v17
	v_xor_b32_e32 v18, 4, v84
	v_cmp_lt_i32_e32 vcc, v18, v21
	s_nop 1
	v_cndmask_b32_e32 v18, v84, v18, vcc
	v_lshlrev_b32_e32 v18, 2, v18
	v_xor_b32_e32 v19, 8, v84
	v_cmp_lt_i32_e32 vcc, v19, v21
	s_nop 1
	v_cndmask_b32_e32 v19, v84, v19, vcc
	v_lshlrev_b32_e32 v19, 2, v19
	v_xor_b32_e32 v20, 16, v84
	v_cmp_lt_i32_e32 vcc, v20, v21
	s_nop 1
	v_cndmask_b32_e32 v20, v84, v20, vcc
	v_lshlrev_b32_e32 v20, 2, v20
	v_cmp_lt_i32_e32 vcc, v23, v21
	v_cndmask_b32_e32 v21, v84, v23, vcc
	v_lshlrev_b32_e32 v21, 2, v21
	v_cvt_pk_bf16_f32 v26, v94, v95
	v_cvt_pk_bf16_f32 v27, v92, v93
	global_store_dwordx4 v[80:81], v[24:27], off offset:1024
	s_and_saveexec_b64 s[46:47], s[4:5]
	s_cbranch_execz .LBB0_1017
	v_mov_b32_e32 v22, s100
	v_fmamk_f32 v22, v22, 0x3a800000, v56
	v_mul_f32_e32 v23, 0x4b800000, v22
	v_cmp_gt_f32_e32 vcc, s51, v22
	s_add_u32 s42, s16, s42
	s_addc_u32 s43, s17, s43
	v_cndmask_b32_e32 v22, v22, v23, vcc
	v_rsq_f32_e32 v22, v22
	s_nop 0
	v_mul_f32_e32 v23, 0x45800000, v22
	v_cndmask_b32_e32 v22, v22, v23, vcc
	global_store_dword v57, v22, s[42:43]
.LBB0_1017:
	s_or_b64 exec, exec, s[46:47]
	s_waitcnt vmcnt(4)
	v_lshlrev_b32_e32 v26, 16, v54
	v_and_b32_e32 v27, 0xffff0000, v54
	s_waitcnt vmcnt(2)
	v_div_scale_f32 v54, s[42:43], v85, v85, 1.0
	v_lshlrev_b32_e32 v28, 16, v55
	v_and_b32_e32 v29, 0xffff0000, v55
	v_rcp_f32_e32 v55, v54
	v_lshlrev_b32_e32 v22, 16, v52
	s_waitcnt lgkmcnt(0)
	v_and_b32_e32 v23, 0xffff0000, v52
	v_lshlrev_b32_e32 v24, 16, v53
	v_fma_f32 v80, -v54, v55, 1.0
	v_fmac_f32_e32 v55, v80, v55
	v_div_scale_f32 v80, vcc, 1.0, v85, 1.0
	v_mul_f32_e32 v81, v80, v55
	v_fma_f32 v87, -v54, v81, v80
	v_fmac_f32_e32 v81, v87, v55
	v_fma_f32 v54, -v54, v81, v80
	v_div_fmas_f32 v54, v54, v55, v81
	v_and_b32_e32 v25, 0xffff0000, v53
	v_lshlrev_b32_e32 v30, 16, v48
	v_and_b32_e32 v31, 0xffff0000, v48
	v_div_fixup_f32 v54, v54, v85, 1.0
	v_pk_mul_f32 v[22:23], v[54:55], v[22:23] op_sel_hi:[0,1]
	v_pk_mul_f32 v[24:25], v[54:55], v[24:25] op_sel_hi:[0,1]
	v_pk_mul_f32 v[26:27], v[54:55], v[26:27] op_sel_hi:[0,1]
	v_pk_mul_f32 v[28:29], v[54:55], v[28:29] op_sel_hi:[0,1]
	v_pk_mul_f32 v[30:31], v[54:55], v[30:31] op_sel_hi:[0,1]
	v_fmamk_f32 v55, v86, 0x3a800000, v56
	v_mul_f32_e32 v80, 0x4b800000, v55
	v_cmp_gt_f32_e32 vcc, s51, v55
	v_lshlrev_b32_e32 v48, 16, v49
	v_and_b32_e32 v49, 0xffff0000, v49
	v_cndmask_b32_e32 v55, v55, v80, vcc
	v_rsq_f32_e32 v55, v55
	v_lshlrev_b32_e32 v52, 16, v50
	v_and_b32_e32 v53, 0xffff0000, v50
	v_lshlrev_b32_e32 v50, 16, v51
	v_and_b32_e32 v51, 0xffff0000, v51
	v_pk_mul_f32 v[48:49], v[54:55], v[48:49] op_sel_hi:[0,1]
	v_pk_mul_f32 v[52:53], v[54:55], v[52:53] op_sel_hi:[0,1]
	v_pk_mul_f32 v[50:51], v[54:55], v[50:51] op_sel_hi:[0,1]
	v_mul_f32_e32 v54, 0x45800000, v55
	v_cndmask_b32_e32 v54, v55, v54, vcc
	v_pk_mul_f32 v[40:41], v[40:41], v[54:55] op_sel_hi:[1,0]
	v_pk_mul_f32 v[42:43], v[42:43], v[54:55] op_sel_hi:[1,0]
	v_pk_mul_f32 v[40:41], v[4:5], v[40:41]
	v_pk_mul_f32 v[42:43], v[6:7], v[42:43]
	v_pk_fma_f32 v[22:23], v[58:59], v[22:23], v[40:41]
	v_pk_mul_f32 v[40:41], v[46:47], v[54:55] op_sel_hi:[1,0]
	v_pk_fma_f32 v[24:25], v[60:61], v[24:25], v[42:43]
	v_pk_mul_f32 v[42:43], v[44:45], v[54:55] op_sel_hi:[1,0]
	v_pk_mul_f32 v[40:41], v[2:3], v[40:41]
	v_pk_mul_f32 v[42:43], v[0:1], v[42:43]
	v_pk_fma_f32 v[28:29], v[64:65], v[28:29], v[40:41]
	v_mul_f32_e32 v40, v23, v23
	v_mul_f32_e32 v41, v25, v25
	v_pk_mul_f32 v[34:35], v[34:35], v[54:55] op_sel_hi:[1,0]
	v_pk_mul_f32 v[32:33], v[32:33], v[54:55] op_sel_hi:[1,0]
	v_pk_fma_f32 v[26:27], v[62:63], v[26:27], v[42:43]
	v_fmac_f32_e32 v40, v22, v22
	v_fmac_f32_e32 v41, v24, v24
	v_pk_mul_f32 v[32:33], v[12:13], v[32:33]
	v_pk_mul_f32 v[34:35], v[14:15], v[34:35]
	v_add_f32_e32 v40, v40, v41
	v_mul_f32_e32 v41, v27, v27
	v_mul_f32_e32 v42, v29, v29
	v_pk_fma_f32 v[34:35], v[68:69], v[48:49], v[34:35]
	v_pk_fma_f32 v[30:31], v[66:67], v[30:31], v[32:33]
	v_fmac_f32_e32 v41, v26, v26
	v_fmac_f32_e32 v42, v28, v28
	v_pk_mul_f32 v[32:33], v[38:39], v[54:55] op_sel_hi:[1,0]
	v_pk_mul_f32 v[36:37], v[36:37], v[54:55] op_sel_hi:[1,0]
	v_mul_f32_e32 v38, v31, v31
	v_mul_f32_e32 v39, v35, v35
	v_add_f32_e32 v41, v41, v42
	v_pk_mul_f32 v[36:37], v[8:9], v[36:37]
	v_pk_mul_f32 v[32:33], v[10:11], v[32:33]
	v_fmac_f32_e32 v38, v30, v30
	v_fmac_f32_e32 v39, v34, v34
	v_add_f32_e32 v40, v40, v41
	v_pk_fma_f32 v[32:33], v[72:73], v[50:51], v[32:33]
	v_pk_fma_f32 v[36:37], v[70:71], v[52:53], v[36:37]
	v_add_f32_e32 v38, v38, v39
	v_add_f32_e32 v38, v38, v40
	v_mul_f32_e32 v39, v37, v37
	v_mul_f32_e32 v40, v33, v33
	v_fmac_f32_e32 v39, v36, v36
	v_fmac_f32_e32 v40, v32, v32
	v_add_f32_e32 v39, v39, v40
	v_add_f32_e32 v38, v39, v38
	v_mov_b32_e32 v243, v38
	s_nop 1
	v_add_f32_dpp v243, v243, v243 quad_perm:[1,0,3,2] row_mask:0xf bank_mask:0xf
	s_nop 1
	v_add_f32_dpp v243, v243, v243 quad_perm:[2,3,0,1] row_mask:0xf bank_mask:0xf
	s_nop 1
	v_add_f32_dpp v243, v243, v243 row_half_mirror row_mask:0xf bank_mask:0xf
	s_nop 1
	v_add_f32_dpp v243, v243, v243 row_mirror row_mask:0xf bank_mask:0xf
	s_nop 1
	v_add_f32_dpp v243, v243, v243 row_bcast:15 row_mask:0xa bank_mask:0xf
	s_nop 1
	v_add_f32_dpp v243, v243, v243 row_bcast:31 row_mask:0xc bank_mask:0xf
	s_nop 1
	v_readlane_b32 s101, v243, 63
	s_nop 1
	v_cvt_pk_bf16_f32 v16, v22, v23
	v_cvt_pk_bf16_f32 v17, v24, v25
	v_cvt_pk_bf16_f32 v18, v26, v27
	v_cvt_pk_bf16_f32 v19, v28, v29
	global_store_dwordx4 v[82:83], v[16:19], off
	s_nop 0
	v_cvt_pk_bf16_f32 v18, v30, v31
	v_cvt_pk_bf16_f32 v19, v34, v35
	v_cvt_pk_bf16_f32 v20, v36, v37
	v_cvt_pk_bf16_f32 v21, v32, v33
	global_store_dwordx4 v[82:83], v[18:21], off offset:1024
	s_and_saveexec_b64 s[42:43], s[4:5]
	s_cbranch_execz .LBB0_1006
	v_mov_b32_e32 v16, s101
	v_fmamk_f32 v16, v16, 0x3a800000, v56
	v_mul_f32_e32 v17, 0x4b800000, v16
	v_cmp_gt_f32_e32 vcc, s51, v16
	s_add_u32 s44, s16, s44
	s_addc_u32 s45, s17, s45
	v_cndmask_b32_e32 v16, v16, v17, vcc
	v_rsq_f32_e32 v16, v16
	s_nop 0
	v_mul_f32_e32 v17, 0x45800000, v16
	v_cndmask_b32_e32 v16, v16, v17, vcc
	global_store_dword v57, v16, s[44:45]
	s_branch .LBB0_1006

.LBB0_1252:
	s_cmpk_gt_i32 s0, 0x7fff
	s_mov_b64 s[68:69], -1
	s_cbranch_scc0 .LBB0_1254
	s_add_i32 s2, s0, 0xffff8000
	s_lshl_b64 s[66:67], s[2:3], 12
	v_lshl_add_u64 v[16:17], v[60:61], 0, s[66:67]
	v_add_co_u32_e32 v42, vcc, 0x400000, v16
	v_lshl_add_u64 v[38:39], v[16:17], 0, s[4:5]
	s_nop 0
	v_addc_co_u32_e32 v43, vcc, 0, v17, vcc
	v_add_co_u32_e32 v78, vcc, 0x800000, v16
	v_lshl_add_u64 v[46:47], v[16:17], 0, s[6:7]
	v_lshl_add_u64 v[54:55], v[16:17], 0, s[8:9]
	v_addc_co_u32_e32 v79, vcc, 0, v17, vcc
	global_load_dwordx4 v[18:21], v[16:17], off offset:16
	global_load_dwordx4 v[22:25], v[16:17], off
	global_load_dwordx4 v[26:29], v[16:17], off offset:2064
	global_load_dwordx4 v[30:33], v[16:17], off offset:2048
	global_load_dwordx4 v[34:37], v[42:43], off
	s_nop 0
	global_load_dwordx4 v[38:41], v[38:39], off offset:16
	s_nop 0
	global_load_dwordx4 v[42:45], v[42:43], off offset:2048
	s_nop 0
	global_load_dwordx4 v[46:49], v[46:47], off offset:16
	s_nop 0
	global_load_dwordx4 v[50:53], v[78:79], off
	global_load_dwordx4 v[74:77], v[54:55], off offset:16
	v_lshl_add_u64 v[54:55], v[16:17], 0, s[10:11]
	global_load_dwordx4 v[78:81], v[78:79], off offset:2048
	s_nop 0
	global_load_dwordx4 v[82:85], v[54:55], off offset:16
	v_add_co_u32_e32 v54, vcc, 0xc00000, v16
	v_lshl_add_u64 v[90:91], v[16:17], 0, s[12:13]
	s_nop 0
	v_addc_co_u32_e32 v55, vcc, 0, v17, vcc
	global_load_dwordx4 v[86:89], v[54:55], off
	s_nop 0
	global_load_dwordx4 v[90:93], v[90:91], off offset:16
	s_nop 0
	global_load_dwordx4 v[94:97], v[54:55], off offset:2048
	v_lshl_add_u64 v[54:55], v[16:17], 0, s[14:15]
	v_add_co_u32_e32 v110, vcc, s72, v16
	global_load_dwordx4 v[98:101], v[54:55], off offset:16
	v_lshl_add_u64 v[54:55], v[16:17], 0, s[16:17]
	v_addc_co_u32_e32 v111, vcc, 0, v17, vcc
	v_lshl_add_u64 v[114:115], v[16:17], 0, s[18:19]
	global_load_dwordx4 v[102:105], v[110:111], off
	global_load_dwordx4 v[106:109], v[54:55], off offset:16
	s_nop 0
	global_load_dwordx4 v[110:113], v[110:111], off offset:2048
	s_nop 0
	global_load_dwordx4 v[114:117], v[114:115], off offset:16
	v_add_co_u32_e32 v54, vcc, s73, v16
	v_lshl_add_u64 v[122:123], v[16:17], 0, s[20:21]
	s_nop 0
	v_addc_co_u32_e32 v55, vcc, 0, v17, vcc
	global_load_dwordx4 v[118:121], v[54:55], off
	s_nop 0
	global_load_dwordx4 v[122:125], v[122:123], off offset:16
	s_nop 0
	global_load_dwordx4 v[126:129], v[54:55], off offset:2048
	v_lshl_add_u64 v[134:135], v[16:17], 0, s[48:49]
	v_lshl_add_u64 v[142:143], v[16:17], 0, s[50:51]
	v_lshl_add_u64 v[150:151], v[16:17], 0, s[52:53]
	v_lshl_add_u64 v[158:159], v[16:17], 0, s[54:55]
	v_lshl_add_u64 v[166:167], v[16:17], 0, s[56:57]
	v_lshl_add_u64 v[174:175], v[16:17], 0, s[58:59]
	v_lshl_add_u64 v[182:183], v[16:17], 0, s[60:61]
	v_lshl_add_u64 v[190:191], v[16:17], 0, s[62:63]
	s_mov_b32 s1, s3
	s_lshl_b64 s[66:67], s[0:1], 11
	s_mov_b64 s[68:69], 0
	s_waitcnt vmcnt(22)
	v_pk_add_f32 v[18:19], v[18:19], 0 op_sel_hi:[1,0]
	v_pk_add_f32 v[20:21], v[20:21], 0 op_sel_hi:[1,0]
	s_waitcnt vmcnt(20)
	v_pk_add_f32 v[26:27], v[26:27], 0 op_sel_hi:[1,0]
	s_waitcnt vmcnt(19)
	v_pk_add_f32 v[30:31], v[30:31], 0 op_sel_hi:[1,0]
	s_waitcnt vmcnt(17)
	v_pk_add_f32 v[18:19], v[18:19], v[38:39]
	v_pk_add_f32 v[20:21], v[20:21], v[40:41]
	s_waitcnt vmcnt(16)
	v_pk_add_f32 v[30:31], v[30:31], v[42:43]
	s_waitcnt vmcnt(13)
	v_pk_add_f32 v[18:19], v[18:19], v[74:75]
	v_pk_add_f32 v[20:21], v[20:21], v[76:77]
	s_waitcnt vmcnt(12)
	v_pk_add_f32 v[30:31], v[30:31], v[78:79]
	v_pk_add_f32 v[26:27], v[26:27], v[46:47]
	v_pk_add_f32 v[22:23], v[22:23], 0 op_sel_hi:[1,0]
	s_waitcnt vmcnt(11)
	v_pk_add_f32 v[26:27], v[26:27], v[82:83]
	v_pk_add_f32 v[22:23], v[22:23], v[34:35]
	s_waitcnt vmcnt(9)
	v_pk_add_f32 v[78:79], v[18:19], v[90:91]
	v_lshl_add_u64 v[18:19], v[16:17], 0, s[22:23]
	v_pk_add_f32 v[76:77], v[20:21], v[92:93]
	global_load_dwordx4 v[18:21], v[18:19], off offset:16
	s_waitcnt vmcnt(9)
	v_pk_add_f32 v[82:83], v[30:31], v[94:95]
	v_add_co_u32_e32 v30, vcc, s74, v16
	v_pk_add_f32 v[22:23], v[22:23], v[50:51]
	s_nop 0
	v_addc_co_u32_e32 v31, vcc, 0, v17, vcc
	v_add_co_u32_e32 v46, vcc, s75, v16
	s_waitcnt vmcnt(5)
	v_pk_add_f32 v[82:83], v[82:83], v[110:111]
	v_addc_co_u32_e32 v47, vcc, 0, v17, vcc
	v_pk_add_f32 v[74:75], v[22:23], v[86:87]
	v_pk_add_f32 v[86:87], v[26:27], v[98:99]
	s_waitcnt vmcnt(1)
	v_pk_add_f32 v[212:213], v[82:83], v[126:127]
	v_add_co_u32_e32 v82, vcc, s76, v16
	v_pk_add_f32 v[202:203], v[86:87], v[114:115]
	s_nop 0
	v_addc_co_u32_e32 v83, vcc, 0, v17, vcc
	v_add_co_u32_e32 v98, vcc, s77, v16
	v_pk_add_f32 v[24:25], v[24:25], 0 op_sel_hi:[1,0]
	s_nop 0
	v_addc_co_u32_e32 v99, vcc, 0, v17, vcc
	v_add_co_u32_e32 v114, vcc, s78, v16
	v_pk_add_f32 v[32:33], v[32:33], 0 op_sel_hi:[1,0]
	v_pk_add_f32 v[28:29], v[28:29], 0 op_sel_hi:[1,0]
	v_addc_co_u32_e32 v115, vcc, 0, v17, vcc
	v_pk_add_f32 v[24:25], v[24:25], v[36:37]
	v_pk_add_f32 v[32:33], v[32:33], v[44:45]
	v_pk_add_f32 v[28:29], v[28:29], v[48:49]
	v_add_co_u32_e32 v130, vcc, s79, v16
	v_pk_add_f32 v[24:25], v[24:25], v[52:53]
	v_pk_add_f32 v[32:33], v[32:33], v[80:81]
	v_pk_add_f32 v[28:29], v[28:29], v[84:85]
	v_lshl_add_u64 v[26:27], v[16:17], 0, s[24:25]
	v_lshl_add_u64 v[34:35], v[16:17], 0, s[26:27]
	v_addc_co_u32_e32 v131, vcc, 0, v17, vcc
	v_pk_add_f32 v[54:55], v[24:25], v[88:89]
	v_pk_add_f32 v[80:81], v[32:33], v[96:97]
	v_pk_add_f32 v[84:85], v[28:29], v[100:101]
	global_load_dwordx4 v[22:25], v[30:31], off
	s_nop 0
	global_load_dwordx4 v[26:29], v[26:27], off offset:16
	s_nop 0
	global_load_dwordx4 v[30:33], v[30:31], off offset:2048
	s_nop 0
	global_load_dwordx4 v[34:37], v[34:35], off offset:16
	v_lshl_add_u64 v[42:43], v[16:17], 0, s[28:29]
	v_lshl_add_u64 v[50:51], v[16:17], 0, s[30:31]
	v_pk_add_f32 v[78:79], v[78:79], v[106:107]
	v_add_co_u32_e32 v146, vcc, s80, v16
	global_load_dwordx4 v[38:41], v[46:47], off
	s_nop 0
	global_load_dwordx4 v[42:45], v[42:43], off offset:16
	s_nop 0
	global_load_dwordx4 v[46:49], v[46:47], off offset:2048
	s_nop 0
	global_load_dwordx4 v[50:53], v[50:51], off offset:16
	v_pk_add_f32 v[74:75], v[74:75], v[102:103]
	v_pk_add_f32 v[76:77], v[76:77], v[108:109]
	v_pk_add_f32 v[80:81], v[80:81], v[112:113]
	v_pk_add_f32 v[208:209], v[78:79], v[122:123]
	v_lshl_add_u64 v[78:79], v[16:17], 0, s[34:35]
	v_lshl_add_u64 v[86:87], v[16:17], 0, s[36:37]
	v_addc_co_u32_e32 v147, vcc, 0, v17, vcc
	v_pk_add_f32 v[194:195], v[84:85], v[116:117]
	v_pk_add_f32 v[204:205], v[74:75], v[118:119]
	v_pk_add_f32 v[206:207], v[76:77], v[124:125]
	v_pk_add_f32 v[210:211], v[80:81], v[128:129]
	global_load_dwordx4 v[74:77], v[82:83], off
	s_nop 0
	global_load_dwordx4 v[78:81], v[78:79], off offset:16
	s_nop 0
	global_load_dwordx4 v[82:85], v[82:83], off offset:2048
	s_nop 0
	global_load_dwordx4 v[86:89], v[86:87], off offset:16
	v_lshl_add_u64 v[94:95], v[16:17], 0, s[38:39]
	v_lshl_add_u64 v[102:103], v[16:17], 0, s[40:41]
	v_add_co_u32_e32 v162, vcc, s81, v16
	v_pk_add_f32 v[54:55], v[54:55], v[104:105]
	global_load_dwordx4 v[90:93], v[98:99], off
	s_nop 0
	global_load_dwordx4 v[94:97], v[94:95], off offset:16
	s_nop 0
	global_load_dwordx4 v[98:101], v[98:99], off offset:2048
	s_nop 0
	global_load_dwordx4 v[102:105], v[102:103], off offset:16
	v_lshl_add_u64 v[110:111], v[16:17], 0, s[42:43]
	v_lshl_add_u64 v[118:119], v[16:17], 0, s[44:45]
	v_addc_co_u32_e32 v163, vcc, 0, v17, vcc
	v_pk_add_f32 v[54:55], v[54:55], v[120:121]
	global_load_dwordx4 v[106:109], v[114:115], off
	s_nop 0
	global_load_dwordx4 v[110:113], v[110:111], off offset:16
	s_nop 0
	global_load_dwordx4 v[114:117], v[114:115], off offset:2048
	s_nop 0
	global_load_dwordx4 v[118:121], v[118:119], off offset:16
	v_lshl_add_u64 v[126:127], v[16:17], 0, s[46:47]
	v_add_co_u32_e32 v178, vcc, s82, v16
	global_load_dwordx4 v[122:125], v[130:131], off
	s_nop 0
	global_load_dwordx4 v[126:129], v[126:127], off offset:16
	s_nop 0
	global_load_dwordx4 v[130:133], v[130:131], off offset:2048
	s_nop 0
	global_load_dwordx4 v[134:137], v[134:135], off offset:16
	v_addc_co_u32_e32 v179, vcc, 0, v17, vcc
	global_load_dwordx4 v[138:141], v[146:147], off
	s_nop 0
	global_load_dwordx4 v[142:145], v[142:143], off offset:16
	s_nop 0
	global_load_dwordx4 v[146:149], v[146:147], off offset:2048
	s_nop 0
	global_load_dwordx4 v[150:153], v[150:151], off offset:16
	v_add_co_u32_e32 v196, vcc, s83, v16
	global_load_dwordx4 v[154:157], v[162:163], off
	s_nop 0
	global_load_dwordx4 v[158:161], v[158:159], off offset:16
	s_nop 0
	global_load_dwordx4 v[162:165], v[162:163], off offset:2048
	s_nop 0
	global_load_dwordx4 v[166:169], v[166:167], off offset:16
	v_addc_co_u32_e32 v197, vcc, 0, v17, vcc
	global_load_dwordx4 v[170:173], v[178:179], off
	s_nop 0
	global_load_dwordx4 v[174:177], v[174:175], off offset:16
	s_nop 0
	global_load_dwordx4 v[178:181], v[178:179], off offset:2048
	s_nop 0
	global_load_dwordx4 v[182:185], v[182:183], off offset:16
	v_lshl_add_u64 v[16:17], v[16:17], 0, s[64:65]
	global_load_dwordx4 v[186:189], v[196:197], off
	s_waitcnt vmcnt(37)
	v_pk_add_f32 v[20:21], v[194:195], v[20:21]
	global_load_dwordx4 v[190:193], v[190:191], off offset:16
	v_cmp_lt_i32_e32 vcc, v68, v67
	global_load_dwordx4 v[194:197], v[196:197], off offset:2048
	s_waitcnt vmcnt(38)
	v_pk_add_f32 v[22:23], v[204:205], v[22:23]
	global_load_dwordx4 v[198:201], v[16:17], off offset:16
	v_pk_add_f32 v[16:17], v[202:203], v[18:19]
	v_pk_add_f32 v[18:19], v[54:55], v[24:25]
	s_waitcnt vmcnt(38)
	v_pk_add_f32 v[24:25], v[206:207], v[28:29]
	v_pk_add_f32 v[26:27], v[208:209], v[26:27]
	s_waitcnt vmcnt(37)
	v_pk_add_f32 v[28:29], v[210:211], v[32:33]
	v_pk_add_f32 v[30:31], v[212:213], v[30:31]
	s_waitcnt vmcnt(36)
	v_pk_add_f32 v[20:21], v[20:21], v[36:37]
	v_pk_add_f32 v[16:17], v[16:17], v[34:35]
	s_waitcnt vmcnt(35)
	v_pk_add_f32 v[18:19], v[18:19], v[40:41]
	v_pk_add_f32 v[22:23], v[22:23], v[38:39]
	s_waitcnt vmcnt(34)
	v_pk_add_f32 v[24:25], v[24:25], v[44:45]
	v_pk_add_f32 v[26:27], v[26:27], v[42:43]
	s_waitcnt vmcnt(33)
	v_pk_add_f32 v[28:29], v[28:29], v[48:49]
	v_pk_add_f32 v[30:31], v[30:31], v[46:47]
	s_waitcnt vmcnt(32)
	v_pk_add_f32 v[20:21], v[20:21], v[52:53]
	v_pk_add_f32 v[16:17], v[16:17], v[50:51]
	s_waitcnt vmcnt(31)
	v_pk_add_f32 v[18:19], v[18:19], v[76:77]
	v_pk_add_f32 v[22:23], v[22:23], v[74:75]
	s_waitcnt vmcnt(30)
	v_pk_add_f32 v[24:25], v[24:25], v[80:81]
	v_pk_add_f32 v[26:27], v[26:27], v[78:79]
	s_waitcnt vmcnt(29)
	v_pk_add_f32 v[28:29], v[28:29], v[84:85]
	v_pk_add_f32 v[30:31], v[30:31], v[82:83]
	s_waitcnt vmcnt(28)
	v_pk_add_f32 v[20:21], v[20:21], v[88:89]
	v_pk_add_f32 v[16:17], v[16:17], v[86:87]
	s_waitcnt vmcnt(27)
	v_pk_add_f32 v[18:19], v[18:19], v[92:93]
	v_pk_add_f32 v[22:23], v[22:23], v[90:91]
	s_waitcnt vmcnt(26)
	v_pk_add_f32 v[24:25], v[24:25], v[96:97]
	v_pk_add_f32 v[26:27], v[26:27], v[94:95]
	s_waitcnt vmcnt(25)
	v_pk_add_f32 v[28:29], v[28:29], v[100:101]
	v_pk_add_f32 v[30:31], v[30:31], v[98:99]
	s_waitcnt vmcnt(24)
	v_pk_add_f32 v[20:21], v[20:21], v[104:105]
	v_pk_add_f32 v[16:17], v[16:17], v[102:103]
	s_waitcnt vmcnt(23)
	v_pk_add_f32 v[18:19], v[18:19], v[108:109]
	v_pk_add_f32 v[22:23], v[22:23], v[106:107]
	s_waitcnt vmcnt(22)
	v_pk_add_f32 v[24:25], v[24:25], v[112:113]
	v_pk_add_f32 v[26:27], v[26:27], v[110:111]
	s_waitcnt vmcnt(21)
	v_pk_add_f32 v[28:29], v[28:29], v[116:117]
	v_pk_add_f32 v[30:31], v[30:31], v[114:115]
	s_waitcnt vmcnt(20)
	v_pk_add_f32 v[20:21], v[20:21], v[120:121]
	v_pk_add_f32 v[16:17], v[16:17], v[118:119]
	s_waitcnt vmcnt(19)
	v_pk_add_f32 v[18:19], v[18:19], v[124:125]
	v_pk_add_f32 v[22:23], v[22:23], v[122:123]
	s_waitcnt vmcnt(18)
	v_pk_add_f32 v[24:25], v[24:25], v[128:129]
	v_pk_add_f32 v[26:27], v[26:27], v[126:127]
	s_waitcnt vmcnt(17)
	v_pk_add_f32 v[28:29], v[28:29], v[132:133]
	v_pk_add_f32 v[30:31], v[30:31], v[130:131]
	s_waitcnt vmcnt(16)
	v_pk_add_f32 v[20:21], v[20:21], v[136:137]
	v_pk_add_f32 v[16:17], v[16:17], v[134:135]
	s_waitcnt vmcnt(15)
	v_pk_add_f32 v[18:19], v[18:19], v[140:141]
	v_pk_add_f32 v[22:23], v[22:23], v[138:139]
	s_waitcnt vmcnt(14)
	v_pk_add_f32 v[24:25], v[24:25], v[144:145]
	v_pk_add_f32 v[26:27], v[26:27], v[142:143]
	s_waitcnt vmcnt(13)
	v_pk_add_f32 v[28:29], v[28:29], v[148:149]
	v_pk_add_f32 v[30:31], v[30:31], v[146:147]
	s_waitcnt vmcnt(12)
	v_pk_add_f32 v[20:21], v[20:21], v[152:153]
	v_pk_add_f32 v[16:17], v[16:17], v[150:151]
	s_waitcnt vmcnt(11)
	v_pk_add_f32 v[18:19], v[18:19], v[156:157]
	v_pk_add_f32 v[22:23], v[22:23], v[154:155]
	s_waitcnt vmcnt(10)
	v_pk_add_f32 v[24:25], v[24:25], v[160:161]
	v_pk_add_f32 v[26:27], v[26:27], v[158:159]
	s_waitcnt vmcnt(9)
	v_pk_add_f32 v[28:29], v[28:29], v[164:165]
	v_pk_add_f32 v[30:31], v[30:31], v[162:163]
	s_waitcnt vmcnt(8)
	v_pk_add_f32 v[20:21], v[20:21], v[168:169]
	v_pk_add_f32 v[16:17], v[16:17], v[166:167]
	s_waitcnt vmcnt(7)
	v_pk_add_f32 v[18:19], v[18:19], v[172:173]
	v_pk_add_f32 v[22:23], v[22:23], v[170:171]
	s_waitcnt vmcnt(6)
	v_pk_add_f32 v[24:25], v[24:25], v[176:177]
	v_pk_add_f32 v[26:27], v[26:27], v[174:175]
	s_waitcnt vmcnt(5)
	v_pk_add_f32 v[28:29], v[28:29], v[180:181]
	v_pk_add_f32 v[30:31], v[30:31], v[178:179]
	s_waitcnt vmcnt(4)
	v_pk_add_f32 v[32:33], v[20:21], v[184:185]
	v_pk_add_f32 v[34:35], v[16:17], v[182:183]
	s_waitcnt vmcnt(3)
	v_pk_add_f32 v[18:19], v[18:19], v[188:189]
	v_pk_add_f32 v[16:17], v[22:23], v[186:187]
	s_waitcnt vmcnt(2)
	v_pk_add_f32 v[22:23], v[24:25], v[192:193]
	v_pk_add_f32 v[20:21], v[26:27], v[190:191]
	s_waitcnt vmcnt(1)
	v_pk_add_f32 v[26:27], v[28:29], v[196:197]
	v_pk_add_f32 v[24:25], v[30:31], v[194:195]
	s_waitcnt vmcnt(0)
	v_pk_add_f32 v[30:31], v[32:33], v[200:201]
	v_pk_add_f32 v[28:29], v[34:35], v[198:199]
	v_pk_mul_f32 v[32:33], v[18:19], v[18:19]
	v_pk_mul_f32 v[34:35], v[16:17], v[16:17]
	s_nop 0
	v_pk_mov_b32 v[36:37], v[34:35], v[32:33] op_sel:[1,0]
	v_mov_b32_e32 v35, v33
	v_pk_add_f32 v[32:33], v[36:37], v[34:35]
	v_pk_mul_f32 v[34:35], v[22:23], v[22:23]
	v_pk_mul_f32 v[36:37], v[20:21], v[20:21]
	v_pk_add_f32 v[32:33], v[32:33], v[32:33] op_sel:[0,1] op_sel_hi:[1,0]
	v_pk_mov_b32 v[38:39], v[36:37], v[34:35] op_sel:[1,0]
	v_mov_b32_e32 v37, v35
	v_pk_add_f32 v[34:35], v[38:39], v[36:37]
	v_mul_f32_e32 v36, v28, v28
	v_mul_f32_e32 v37, v29, v29
	v_pk_add_f32 v[34:35], v[34:35], v[34:35] op_sel:[0,1] op_sel_hi:[1,0]
	v_mov_b32_e32 v33, v36
	v_mov_b32_e32 v35, v37
	v_pk_add_f32 v[32:33], v[32:33], v[34:35]
	v_mul_f32_e32 v34, v25, v25
	v_mul_f32_e32 v36, v27, v27
	v_mul_f32_e32 v38, v30, v30
	v_mul_f32_e32 v39, v31, v31
	v_pk_fma_f32 v[34:35], v[24:25], v[24:25], v[34:35] op_sel_hi:[1,1,0]
	v_pk_fma_f32 v[36:37], v[26:27], v[26:27], v[36:37] op_sel_hi:[1,1,0]
	v_mov_b32_e32 v35, v38
	v_mov_b32_e32 v37, v39
	v_pk_add_f32 v[34:35], v[34:35], v[36:37]
	s_nop 0
	v_pk_add_f32 v[32:33], v[32:33], v[34:35]
	s_nop 0
	v_add_f32_e32 v32, v32, v33
	v_cndmask_b32_e32 v33, v66, v68, vcc
	v_lshlrev_b32_e32 v33, 2, v33
	v_mov_b32_e32 v240, v32
	s_nop 1
	v_add_f32_dpp v240, v240, v240 quad_perm:[1,0,3,2] row_mask:0xf bank_mask:0xf
	s_nop 1
	v_add_f32_dpp v240, v240, v240 quad_perm:[2,3,0,1] row_mask:0xf bank_mask:0xf
	s_nop 1
	v_add_f32_dpp v240, v240, v240 row_half_mirror row_mask:0xf bank_mask:0xf
	s_nop 1
	v_add_f32_dpp v240, v240, v240 row_mirror row_mask:0xf bank_mask:0xf
	s_nop 1
	v_add_f32_dpp v240, v240, v240 row_bcast:15 row_mask:0xa bank_mask:0xf
	s_nop 1
	v_add_f32_dpp v240, v240, v240 row_bcast:31 row_mask:0xc bank_mask:0xf
	s_nop 1
	v_readlane_b32 s98, v240, 63
	s_nop 1
	v_cmp_lt_i32_e32 vcc, v69, v67
	v_cndmask_b32_e32 v33, v66, v69, vcc
	v_lshlrev_b32_e32 v33, 2, v33
	v_cmp_lt_i32_e32 vcc, v70, v67
	v_cndmask_b32_e32 v33, v66, v70, vcc
	v_lshlrev_b32_e32 v33, 2, v33
	v_cmp_lt_i32_e32 vcc, v71, v67
	v_cndmask_b32_e32 v33, v66, v71, vcc
	v_lshlrev_b32_e32 v33, 2, v33
	v_cmp_lt_i32_e32 vcc, v72, v67
	v_cndmask_b32_e32 v33, v66, v72, vcc
	v_lshlrev_b32_e32 v33, 2, v33
	v_cmp_lt_i32_e32 vcc, v73, v67
	v_cndmask_b32_e32 v33, v66, v73, vcc
	v_lshlrev_b32_e32 v33, 2, v33
	v_mov_b32_e32 v74, s98

.LBB0_1256:
	v_lshl_add_u64 v[32:33], v[58:59], 0, s[66:67]
	global_load_dwordx4 v[36:39], v[32:33], off
	s_nop 0
	global_load_dwordx4 v[32:35], v[32:33], off offset:1024
	s_add_i32 s84, s0, s85
	s_cmp_lt_i32 s84, 0x8400
	s_cselect_b32 s66, s84, s0
	s_cmp_lt_i32 s66, 0x8000
	s_mov_b64 s[70:71], -1
	s_cbranch_scc1 .LBB0_1258
	s_add_i32 s2, s66, 0xffff8000
	s_lshl_b64 s[68:69], s[2:3], 12
	v_lshl_add_u64 v[40:41], v[60:61], 0, s[68:69]
	v_add_co_u32_e32 v88, vcc, 0x400000, v40
	v_lshl_add_u64 v[54:55], v[40:41], 0, s[4:5]
	s_nop 0
	v_addc_co_u32_e32 v89, vcc, 0, v41, vcc
	global_load_dwordx4 v[42:45], v[40:41], off offset:16
	global_load_dwordx4 v[46:49], v[40:41], off
	global_load_dwordx4 v[50:53], v[40:41], off offset:2064
	global_load_dwordx4 v[76:79], v[40:41], off offset:2048
	global_load_dwordx4 v[80:83], v[88:89], off
	global_load_dwordx4 v[84:87], v[54:55], off offset:16
	v_lshl_add_u64 v[54:55], v[40:41], 0, s[6:7]
	v_add_co_u32_e32 v104, vcc, 0x800000, v40
	global_load_dwordx4 v[88:91], v[88:89], off offset:2048
	s_nop 0
	global_load_dwordx4 v[92:95], v[54:55], off offset:16
	v_lshl_add_u64 v[54:55], v[40:41], 0, s[8:9]
	v_addc_co_u32_e32 v105, vcc, 0, v41, vcc
	global_load_dwordx4 v[96:99], v[104:105], off
	global_load_dwordx4 v[100:103], v[54:55], off offset:16
	v_lshl_add_u64 v[54:55], v[40:41], 0, s[10:11]
	global_load_dwordx4 v[104:107], v[104:105], off offset:2048
	s_nop 0
	global_load_dwordx4 v[108:111], v[54:55], off offset:16
	v_add_co_u32_e32 v54, vcc, 0xc00000, v40
	v_lshl_add_u64 v[116:117], v[40:41], 0, s[12:13]
	s_nop 0
	v_addc_co_u32_e32 v55, vcc, 0, v41, vcc
	global_load_dwordx4 v[112:115], v[54:55], off
	s_nop 0
	global_load_dwordx4 v[116:119], v[116:117], off offset:16
	s_nop 0
	global_load_dwordx4 v[120:123], v[54:55], off offset:2048
	v_lshl_add_u64 v[54:55], v[40:41], 0, s[14:15]
	v_add_co_u32_e32 v136, vcc, s72, v40
	global_load_dwordx4 v[124:127], v[54:55], off offset:16
	v_lshl_add_u64 v[54:55], v[40:41], 0, s[16:17]
	v_addc_co_u32_e32 v137, vcc, 0, v41, vcc
	v_lshl_add_u64 v[140:141], v[40:41], 0, s[18:19]
	global_load_dwordx4 v[128:131], v[136:137], off
	global_load_dwordx4 v[132:135], v[54:55], off offset:16
	s_nop 0
	global_load_dwordx4 v[136:139], v[136:137], off offset:2048
	s_nop 0
	global_load_dwordx4 v[140:143], v[140:141], off offset:16
	v_add_co_u32_e32 v54, vcc, s73, v40
	v_lshl_add_u64 v[148:149], v[40:41], 0, s[20:21]
	s_nop 0
	v_addc_co_u32_e32 v55, vcc, 0, v41, vcc
	global_load_dwordx4 v[144:147], v[54:55], off
	s_nop 0
	global_load_dwordx4 v[148:151], v[148:149], off offset:16
	s_nop 0
	global_load_dwordx4 v[152:155], v[54:55], off offset:2048
	v_lshl_add_u64 v[160:161], v[40:41], 0, s[48:49]
	v_lshl_add_u64 v[168:169], v[40:41], 0, s[50:51]
	v_lshl_add_u64 v[176:177], v[40:41], 0, s[52:53]
	v_lshl_add_u64 v[184:185], v[40:41], 0, s[54:55]
	v_lshl_add_u64 v[192:193], v[40:41], 0, s[56:57]
	v_lshl_add_u64 v[200:201], v[40:41], 0, s[58:59]
	v_lshl_add_u64 v[208:209], v[40:41], 0, s[60:61]
	v_lshl_add_u64 v[216:217], v[40:41], 0, s[62:63]
	s_mov_b32 s67, s3
	s_lshl_b64 s[68:69], s[66:67], 11
	s_mov_b64 s[70:71], 0
	s_waitcnt vmcnt(22)
	v_pk_add_f32 v[42:43], v[42:43], 0 op_sel_hi:[1,0]
	v_pk_add_f32 v[44:45], v[44:45], 0 op_sel_hi:[1,0]
	s_waitcnt vmcnt(20)
	v_pk_add_f32 v[50:51], v[50:51], 0 op_sel_hi:[1,0]
	s_waitcnt vmcnt(19)
	v_pk_add_f32 v[54:55], v[78:79], 0 op_sel_hi:[1,0]
	s_waitcnt vmcnt(17)
	v_pk_add_f32 v[42:43], v[42:43], v[84:85]
	v_pk_add_f32 v[76:77], v[76:77], 0 op_sel_hi:[1,0]
	v_pk_add_f32 v[44:45], v[44:45], v[86:87]
	s_waitcnt vmcnt(16)
	v_pk_add_f32 v[54:55], v[54:55], v[90:91]
	v_pk_add_f32 v[76:77], v[76:77], v[88:89]
	s_waitcnt vmcnt(15)
	v_pk_add_f32 v[50:51], v[50:51], v[92:93]
	v_pk_add_f32 v[46:47], v[46:47], 0 op_sel_hi:[1,0]
	v_pk_add_f32 v[48:49], v[48:49], 0 op_sel_hi:[1,0]
	s_waitcnt vmcnt(13)
	v_pk_add_f32 v[42:43], v[42:43], v[100:101]
	v_pk_add_f32 v[44:45], v[44:45], v[102:103]
	s_waitcnt vmcnt(12)
	v_pk_add_f32 v[54:55], v[54:55], v[106:107]
	v_pk_add_f32 v[76:77], v[76:77], v[104:105]
	s_waitcnt vmcnt(11)
	v_pk_add_f32 v[50:51], v[50:51], v[108:109]
	v_pk_add_f32 v[46:47], v[46:47], v[80:81]
	v_pk_add_f32 v[52:53], v[52:53], 0 op_sel_hi:[1,0]
	v_pk_add_f32 v[46:47], v[46:47], v[96:97]
	s_waitcnt vmcnt(9)
	v_pk_add_f32 v[106:107], v[42:43], v[116:117]
	v_lshl_add_u64 v[42:43], v[40:41], 0, s[22:23]
	v_pk_add_f32 v[104:105], v[44:45], v[118:119]
	global_load_dwordx4 v[42:45], v[42:43], off offset:16
	s_waitcnt vmcnt(9)
	v_pk_add_f32 v[108:109], v[76:77], v[120:121]
	v_add_co_u32_e32 v76, vcc, s74, v40
	v_pk_add_f32 v[102:103], v[46:47], v[112:113]
	s_nop 0
	v_addc_co_u32_e32 v77, vcc, 0, v41, vcc
	v_add_co_u32_e32 v92, vcc, s75, v40
	s_waitcnt vmcnt(5)
	v_pk_add_f32 v[108:109], v[108:109], v[136:137]
	v_addc_co_u32_e32 v93, vcc, 0, v41, vcc
	v_pk_add_f32 v[112:113], v[50:51], v[124:125]
	v_pk_add_f32 v[48:49], v[48:49], v[82:83]
	s_waitcnt vmcnt(1)
	v_pk_add_f32 v[238:239], v[108:109], v[152:153]
	v_add_co_u32_e32 v108, vcc, s76, v40
	v_pk_add_f32 v[228:229], v[112:113], v[140:141]
	s_nop 0
	v_addc_co_u32_e32 v109, vcc, 0, v41, vcc
	v_add_co_u32_e32 v124, vcc, s77, v40
	v_pk_add_f32 v[52:53], v[52:53], v[94:95]
	s_nop 0
	v_addc_co_u32_e32 v125, vcc, 0, v41, vcc
	v_add_co_u32_e32 v140, vcc, s78, v40
	v_pk_add_f32 v[48:49], v[48:49], v[98:99]
	s_nop 0
	v_addc_co_u32_e32 v141, vcc, 0, v41, vcc
	v_add_co_u32_e32 v156, vcc, s79, v40
	v_pk_add_f32 v[52:53], v[52:53], v[110:111]
	v_lshl_add_u64 v[50:51], v[40:41], 0, s[24:25]
	v_addc_co_u32_e32 v157, vcc, 0, v41, vcc
	v_pk_add_f32 v[100:101], v[48:49], v[114:115]
	v_pk_add_f32 v[110:111], v[52:53], v[126:127]
	global_load_dwordx4 v[46:49], v[76:77], off
	s_nop 0
	global_load_dwordx4 v[50:53], v[50:51], off offset:16
	v_lshl_add_u64 v[80:81], v[40:41], 0, s[26:27]
	v_lshl_add_u64 v[88:89], v[40:41], 0, s[28:29]
	v_pk_add_f32 v[104:105], v[104:105], v[134:135]
	v_add_co_u32_e32 v172, vcc, s80, v40
	global_load_dwordx4 v[76:79], v[76:77], off offset:2048
	s_nop 0
	global_load_dwordx4 v[80:83], v[80:81], off offset:16
	s_nop 0
	global_load_dwordx4 v[84:87], v[92:93], off
	s_nop 0
	global_load_dwordx4 v[88:91], v[88:89], off offset:16
	v_lshl_add_u64 v[96:97], v[40:41], 0, s[30:31]
	v_pk_add_f32 v[100:101], v[100:101], v[130:131]
	v_pk_add_f32 v[102:103], v[102:103], v[128:129]
	v_pk_add_f32 v[106:107], v[106:107], v[132:133]
	v_pk_add_f32 v[234:235], v[104:105], v[150:151]
	v_lshl_add_u64 v[104:105], v[40:41], 0, s[34:35]
	v_addc_co_u32_e32 v173, vcc, 0, v41, vcc
	global_load_dwordx4 v[92:95], v[92:93], off offset:2048
	s_nop 0
	global_load_dwordx4 v[96:99], v[96:97], off offset:16
	v_pk_add_f32 v[230:231], v[100:101], v[146:147]
	v_pk_add_f32 v[232:233], v[102:103], v[144:145]
	v_pk_add_f32 v[236:237], v[106:107], v[148:149]
	global_load_dwordx4 v[100:103], v[108:109], off
	s_nop 0
	global_load_dwordx4 v[104:107], v[104:105], off offset:16
	v_lshl_add_u64 v[112:113], v[40:41], 0, s[36:37]
	v_lshl_add_u64 v[120:121], v[40:41], 0, s[38:39]
	v_add_co_u32_e32 v188, vcc, s81, v40
	v_pk_add_f32 v[54:55], v[54:55], v[122:123]
	v_pk_add_f32 v[220:221], v[110:111], v[142:143]
	global_load_dwordx4 v[108:111], v[108:109], off offset:2048
	s_nop 0
	global_load_dwordx4 v[112:115], v[112:113], off offset:16
	s_nop 0
	global_load_dwordx4 v[116:119], v[124:125], off
	s_nop 0
	global_load_dwordx4 v[120:123], v[120:121], off offset:16
	v_lshl_add_u64 v[128:129], v[40:41], 0, s[40:41]
	v_lshl_add_u64 v[136:137], v[40:41], 0, s[42:43]
	v_addc_co_u32_e32 v189, vcc, 0, v41, vcc
	v_pk_add_f32 v[54:55], v[54:55], v[138:139]
	global_load_dwordx4 v[124:127], v[124:125], off offset:2048
	s_nop 0
	global_load_dwordx4 v[128:131], v[128:129], off offset:16
	s_nop 0
	global_load_dwordx4 v[132:135], v[140:141], off
	s_nop 0
	global_load_dwordx4 v[136:139], v[136:137], off offset:16
	v_lshl_add_u64 v[144:145], v[40:41], 0, s[44:45]
	v_lshl_add_u64 v[152:153], v[40:41], 0, s[46:47]
	v_add_co_u32_e32 v204, vcc, s82, v40
	v_pk_add_f32 v[54:55], v[54:55], v[154:155]
	global_load_dwordx4 v[140:143], v[140:141], off offset:2048
	s_nop 0
	global_load_dwordx4 v[144:147], v[144:145], off offset:16
	s_nop 0
	global_load_dwordx4 v[148:151], v[156:157], off
	s_nop 0
	global_load_dwordx4 v[152:155], v[152:153], off offset:16
	v_addc_co_u32_e32 v205, vcc, 0, v41, vcc
	global_load_dwordx4 v[156:159], v[156:157], off offset:2048
	s_nop 0
	global_load_dwordx4 v[160:163], v[160:161], off offset:16
	s_nop 0
	global_load_dwordx4 v[164:167], v[172:173], off
	s_nop 0
	global_load_dwordx4 v[168:171], v[168:169], off offset:16
	v_add_co_u32_e32 v222, vcc, s83, v40
	global_load_dwordx4 v[172:175], v[172:173], off offset:2048
	s_nop 0
	global_load_dwordx4 v[176:179], v[176:177], off offset:16
	s_nop 0
	global_load_dwordx4 v[180:183], v[188:189], off
	s_nop 0
	global_load_dwordx4 v[184:187], v[184:185], off offset:16
	v_addc_co_u32_e32 v223, vcc, 0, v41, vcc
	global_load_dwordx4 v[188:191], v[188:189], off offset:2048
	s_nop 0
	global_load_dwordx4 v[192:195], v[192:193], off offset:16
	s_nop 0
	global_load_dwordx4 v[196:199], v[204:205], off
	s_nop 0
	global_load_dwordx4 v[200:203], v[200:201], off offset:16
	s_nop 0
	global_load_dwordx4 v[204:207], v[204:205], off offset:2048
	s_nop 0
	global_load_dwordx4 v[208:211], v[208:209], off offset:16
	s_waitcnt vmcnt(36)
	v_pk_add_f32 v[44:45], v[220:221], v[44:45]
	global_load_dwordx4 v[212:215], v[222:223], off
	v_lshl_add_u64 v[40:41], v[40:41], 0, s[64:65]
	global_load_dwordx4 v[216:219], v[216:217], off offset:16
	v_cmp_lt_i32_e32 vcc, v68, v67
	global_load_dwordx4 v[220:223], v[222:223], off offset:2048
	s_waitcnt vmcnt(38)
	v_pk_add_f32 v[46:47], v[232:233], v[46:47]
	global_load_dwordx4 v[224:227], v[40:41], off offset:16
	v_pk_add_f32 v[40:41], v[228:229], v[42:43]
	v_pk_add_f32 v[42:43], v[230:231], v[48:49]
	s_waitcnt vmcnt(38)
	v_pk_add_f32 v[48:49], v[234:235], v[52:53]
	v_pk_add_f32 v[50:51], v[236:237], v[50:51]
	s_waitcnt vmcnt(37)
	v_pk_add_f32 v[52:53], v[54:55], v[78:79]
	s_waitcnt vmcnt(35)
	v_pk_add_f32 v[42:43], v[42:43], v[86:87]
	v_pk_add_f32 v[46:47], v[46:47], v[84:85]
	v_pk_add_f32 v[54:55], v[238:239], v[76:77]
	s_waitcnt vmcnt(34)
	v_pk_add_f32 v[48:49], v[48:49], v[90:91]
	v_pk_add_f32 v[50:51], v[50:51], v[88:89]
	v_pk_add_f32 v[44:45], v[44:45], v[82:83]
	v_pk_add_f32 v[40:41], v[40:41], v[80:81]
	s_waitcnt vmcnt(33)
	v_pk_add_f32 v[52:53], v[52:53], v[94:95]
	v_pk_add_f32 v[54:55], v[54:55], v[92:93]
	s_waitcnt vmcnt(32)
	v_pk_add_f32 v[44:45], v[44:45], v[98:99]
	v_pk_add_f32 v[40:41], v[40:41], v[96:97]
	s_waitcnt vmcnt(31)
	v_pk_add_f32 v[42:43], v[42:43], v[102:103]
	v_pk_add_f32 v[46:47], v[46:47], v[100:101]
	s_waitcnt vmcnt(30)
	v_pk_add_f32 v[48:49], v[48:49], v[106:107]
	v_pk_add_f32 v[50:51], v[50:51], v[104:105]
	s_waitcnt vmcnt(29)
	v_pk_add_f32 v[52:53], v[52:53], v[110:111]
	s_waitcnt vmcnt(27)
	v_pk_add_f32 v[42:43], v[42:43], v[118:119]
	v_pk_add_f32 v[46:47], v[46:47], v[116:117]
	v_pk_add_f32 v[54:55], v[54:55], v[108:109]
	s_waitcnt vmcnt(26)
	v_pk_add_f32 v[48:49], v[48:49], v[122:123]
	v_pk_add_f32 v[50:51], v[50:51], v[120:121]
	v_pk_add_f32 v[44:45], v[44:45], v[114:115]
	s_waitcnt vmcnt(25)
	v_pk_add_f32 v[52:53], v[52:53], v[126:127]
	s_waitcnt vmcnt(23)
	v_pk_add_f32 v[42:43], v[42:43], v[134:135]
	v_pk_add_f32 v[46:47], v[46:47], v[132:133]
	v_pk_add_f32 v[54:55], v[54:55], v[124:125]
	s_waitcnt vmcnt(22)
	v_pk_add_f32 v[48:49], v[48:49], v[138:139]
	v_pk_add_f32 v[50:51], v[50:51], v[136:137]
	v_pk_add_f32 v[40:41], v[40:41], v[112:113]
	s_waitcnt vmcnt(21)
	v_pk_add_f32 v[52:53], v[52:53], v[142:143]
	s_waitcnt vmcnt(19)
	v_pk_add_f32 v[42:43], v[42:43], v[150:151]
	v_pk_add_f32 v[46:47], v[46:47], v[148:149]
	v_pk_add_f32 v[54:55], v[54:55], v[140:141]
	s_waitcnt vmcnt(18)
	v_pk_add_f32 v[48:49], v[48:49], v[154:155]
	v_pk_add_f32 v[50:51], v[50:51], v[152:153]
	s_waitcnt vmcnt(15)
	v_pk_add_f32 v[42:43], v[42:43], v[166:167]
	v_pk_add_f32 v[46:47], v[46:47], v[164:165]
	v_pk_add_f32 v[52:53], v[52:53], v[158:159]
	v_pk_add_f32 v[54:55], v[54:55], v[156:157]
	s_waitcnt vmcnt(14)
	v_pk_add_f32 v[48:49], v[48:49], v[170:171]
	v_pk_add_f32 v[50:51], v[50:51], v[168:169]
	s_waitcnt vmcnt(11)
	v_pk_add_f32 v[42:43], v[42:43], v[182:183]
	v_pk_add_f32 v[46:47], v[46:47], v[180:181]
	v_pk_add_f32 v[44:45], v[44:45], v[130:131]
	v_pk_add_f32 v[40:41], v[40:41], v[128:129]
	v_pk_add_f32 v[52:53], v[52:53], v[174:175]
	v_pk_add_f32 v[54:55], v[54:55], v[172:173]
	s_waitcnt vmcnt(10)
	v_pk_add_f32 v[48:49], v[48:49], v[186:187]
	v_pk_add_f32 v[50:51], v[50:51], v[184:185]
	s_waitcnt vmcnt(7)
	v_pk_add_f32 v[42:43], v[42:43], v[198:199]
	v_pk_add_f32 v[46:47], v[46:47], v[196:197]
	v_pk_add_f32 v[44:45], v[44:45], v[146:147]
	v_pk_add_f32 v[40:41], v[40:41], v[144:145]
	v_pk_add_f32 v[52:53], v[52:53], v[190:191]
	v_pk_add_f32 v[54:55], v[54:55], v[188:189]
	s_waitcnt vmcnt(6)
	v_pk_add_f32 v[76:77], v[48:49], v[202:203]
	v_pk_add_f32 v[78:79], v[50:51], v[200:201]
	s_waitcnt vmcnt(3)
	v_pk_add_f32 v[50:51], v[42:43], v[214:215]
	v_pk_add_f32 v[48:49], v[46:47], v[212:213]
	v_pk_add_f32 v[44:45], v[44:45], v[162:163]
	v_pk_add_f32 v[40:41], v[40:41], v[160:161]
	v_pk_add_f32 v[80:81], v[52:53], v[206:207]
	v_pk_add_f32 v[82:83], v[54:55], v[204:205]
	s_waitcnt vmcnt(2)
	v_pk_add_f32 v[54:55], v[76:77], v[218:219]
	v_pk_add_f32 v[52:53], v[78:79], v[216:217]
	v_pk_mul_f32 v[76:77], v[50:51], v[50:51]
	v_pk_mul_f32 v[78:79], v[48:49], v[48:49]
	v_pk_add_f32 v[44:45], v[44:45], v[178:179]
	v_pk_add_f32 v[40:41], v[40:41], v[176:177]
	s_waitcnt vmcnt(1)
	v_pk_add_f32 v[42:43], v[80:81], v[222:223]
	v_pk_mov_b32 v[80:81], v[78:79], v[76:77] op_sel:[1,0]
	v_mov_b32_e32 v79, v77
	v_pk_add_f32 v[44:45], v[44:45], v[194:195]
	v_pk_add_f32 v[40:41], v[40:41], v[192:193]
	v_pk_add_f32 v[76:77], v[80:81], v[78:79]
	v_pk_mul_f32 v[78:79], v[54:55], v[54:55]
	v_pk_mul_f32 v[80:81], v[52:53], v[52:53]
	v_pk_add_f32 v[44:45], v[44:45], v[210:211]
	v_pk_add_f32 v[84:85], v[40:41], v[208:209]
	v_pk_add_f32 v[40:41], v[82:83], v[220:221]
	v_pk_mov_b32 v[82:83], v[80:81], v[78:79] op_sel:[1,0]
	v_mov_b32_e32 v81, v79
	s_waitcnt vmcnt(0)
	v_pk_add_f32 v[46:47], v[44:45], v[226:227]
	v_pk_add_f32 v[44:45], v[84:85], v[224:225]
	v_pk_add_f32 v[78:79], v[82:83], v[80:81]
	v_mul_f32_e32 v75, v44, v44
	v_mul_f32_e32 v80, v45, v45
	v_pk_add_f32 v[76:77], v[76:77], v[76:77] op_sel:[0,1] op_sel_hi:[1,0]
	v_pk_add_f32 v[78:79], v[78:79], v[78:79] op_sel:[0,1] op_sel_hi:[1,0]
	v_mov_b32_e32 v77, v75
	v_mov_b32_e32 v79, v80
	v_pk_add_f32 v[76:77], v[76:77], v[78:79]
	v_mul_f32_e32 v78, v41, v41
	v_mul_f32_e32 v81, v46, v46
	v_pk_fma_f32 v[78:79], v[40:41], v[40:41], v[78:79] op_sel_hi:[1,1,0]
	v_mul_f32_e32 v80, v43, v43
	v_mul_f32_e32 v82, v47, v47
	v_mov_b32_e32 v79, v81
	v_pk_fma_f32 v[80:81], v[42:43], v[42:43], v[80:81] op_sel_hi:[1,1,0]
	s_nop 0
	v_mov_b32_e32 v81, v82
	v_pk_add_f32 v[78:79], v[78:79], v[80:81]
	s_nop 0
	v_pk_add_f32 v[76:77], v[76:77], v[78:79]
	s_nop 0
	v_add_f32_e32 v75, v76, v77
	v_cndmask_b32_e32 v76, v66, v68, vcc
	v_lshlrev_b32_e32 v76, 2, v76
	v_mov_b32_e32 v241, v75
	s_nop 1
	v_add_f32_dpp v241, v241, v241 quad_perm:[1,0,3,2] row_mask:0xf bank_mask:0xf
	s_nop 1
	v_add_f32_dpp v241, v241, v241 quad_perm:[2,3,0,1] row_mask:0xf bank_mask:0xf
	s_nop 1
	v_add_f32_dpp v241, v241, v241 row_half_mirror row_mask:0xf bank_mask:0xf
	s_nop 1
	v_add_f32_dpp v241, v241, v241 row_mirror row_mask:0xf bank_mask:0xf
	s_nop 1
	v_add_f32_dpp v241, v241, v241 row_bcast:15 row_mask:0xa bank_mask:0xf
	s_nop 1
	v_add_f32_dpp v241, v241, v241 row_bcast:31 row_mask:0xc bank_mask:0xf
	s_nop 1
	v_readlane_b32 s99, v241, 63
	s_nop 1
	v_cmp_lt_i32_e32 vcc, v69, v67
	v_cndmask_b32_e32 v76, v66, v69, vcc
	v_lshlrev_b32_e32 v76, 2, v76
	v_cmp_lt_i32_e32 vcc, v70, v67
	v_cndmask_b32_e32 v76, v66, v70, vcc
	v_lshlrev_b32_e32 v76, 2, v76
	v_cmp_lt_i32_e32 vcc, v71, v67
	v_cndmask_b32_e32 v76, v66, v71, vcc
	v_lshlrev_b32_e32 v76, 2, v76
	v_cmp_lt_i32_e32 vcc, v72, v67
	v_cndmask_b32_e32 v76, v66, v72, vcc
	v_lshlrev_b32_e32 v76, 2, v76
	v_cmp_lt_i32_e32 vcc, v73, v67
	v_cndmask_b32_e32 v76, v66, v73, vcc
	v_lshlrev_b32_e32 v76, 2, v76
	v_mov_b32_e32 v75, s99
